# prep phase: row prefetch loads on a scalar row base with immediate offsets; skip-branches around always-populated masked store blocks removed
# speedup vs baseline: 1.0050x; 1.0027x over previous
.LBB0_167:
	s_add_i32 s55, s55, s54
	s_cmpk_lt_i32 s55, 0x400
	s_cselect_b64 s[46:47], -1, 0
	s_cmpk_gt_i32 s55, 0x3ff
	v_mov_b32_e32 v111, v152
	s_cselect_b64 s[42:43], -1, 0
	s_nop 0
	v_cmp_gt_i32_e32 vcc, s57, v111
	v_lshlrev_b32_e32 v54, 1, v111
	s_barrier
	s_and_saveexec_b64 s[44:45], vcc
	s_cbranch_execz .LBB0_301
	s_waitcnt vmcnt(21)
	v_and_b32_e32 v57, 0xffff0000, v1
	v_lshlrev_b32_e32 v56, 16, v1
	v_and_b32_e32 v59, 0xffff0000, v0
	v_lshlrev_b32_e32 v58, 16, v0
	v_pk_add_f32 v[58:59], v[58:59], v[56:57] neg_lo:[0,1] neg_hi:[0,1]
	v_cmp_lt_i32_e64 s[6:7], s58, v111
	v_cmp_lt_u32_e64 s[4:5], s59, v111
	v_cmp_lt_u32_e32 vcc, s60, v111
	s_waitcnt vmcnt(5)
	v_pk_fma_f32 v[58:59], v[50:51], v[58:59], v[56:57]
	s_and_saveexec_b64 s[48:49], s[6:7]
	s_cbranch_execz .LBB0_176
	s_and_saveexec_b64 s[40:41], s[4:5]
	s_xor_b64 s[50:51], exec, s[40:41]
	s_cbranch_execz .LBB0_173
	s_and_saveexec_b64 s[52:53], vcc

	v_mul_f32_e32 v52, 0xbfb8aa3b, v58
	v_mul_f32_e32 v55, 0xbfb8aa3b, v59
	v_exp_f32_e32 v52, v52
	v_exp_f32_e32 v55, v55
	v_add_f32_e32 v52, 1.0, v52
	v_add_f32_e32 v55, 1.0, v55
	v_rcp_f32_e32 v58, v52
	v_rcp_f32_e32 v59, v55

.LBB0_176:
	s_or_b64 exec, exec, s[48:49]
	v_lshl_add_u32 v52, v54, 2, 0
	ds_write_b64 v52, v[58:59]
	v_and_b32_e32 v59, 0xffff0000, v2
	v_lshlrev_b32_e32 v58, 16, v2
	v_pk_add_f32 v[56:57], v[56:57], v[58:59] neg_lo:[0,1] neg_hi:[0,1]
	s_nop 0
	v_pk_fma_f32 v[56:57], v[50:51], v[56:57], v[58:59]
	s_and_saveexec_b64 s[48:49], s[6:7]
	s_cbranch_execz .LBB0_184
	s_and_saveexec_b64 s[40:41], s[4:5]
	s_xor_b64 s[50:51], exec, s[40:41]
	s_cbranch_execz .LBB0_181
	s_and_saveexec_b64 s[52:53], vcc

	v_mul_f32_e32 v55, 0xbfb8aa3b, v56
	v_mul_f32_e32 v56, 0xbfb8aa3b, v57
	v_exp_f32_e32 v55, v55
	v_exp_f32_e32 v56, v56
	v_add_f32_e32 v55, 1.0, v55
	v_add_f32_e32 v57, 1.0, v56
	v_rcp_f32_e32 v56, v55
	v_rcp_f32_e32 v57, v57

.LBB0_184:
	s_or_b64 exec, exec, s[48:49]
	ds_write_b64 v52, v[56:57] offset:3600
	v_and_b32_e32 v57, 0xffff0000, v3
	v_lshlrev_b32_e32 v56, 16, v3
	v_pk_add_f32 v[58:59], v[58:59], v[56:57] neg_lo:[0,1] neg_hi:[0,1]
	s_nop 0
	v_pk_fma_f32 v[58:59], v[50:51], v[58:59], v[56:57]
	s_and_saveexec_b64 s[48:49], s[6:7]
	s_cbranch_execz .LBB0_192
	s_and_saveexec_b64 s[40:41], s[4:5]
	s_xor_b64 s[50:51], exec, s[40:41]
	s_cbranch_execz .LBB0_189
	s_and_saveexec_b64 s[52:53], vcc

	v_mul_f32_e32 v55, 0xbfb8aa3b, v58
	v_mul_f32_e32 v58, 0xbfb8aa3b, v59
	v_exp_f32_e32 v55, v55
	v_exp_f32_e32 v58, v58
	v_add_f32_e32 v55, 1.0, v55
	v_add_f32_e32 v59, 1.0, v58
	v_rcp_f32_e32 v58, v55
	v_rcp_f32_e32 v59, v59

.LBB0_192:
	s_or_b64 exec, exec, s[48:49]
	ds_write_b64 v52, v[58:59] offset:7200
	v_and_b32_e32 v59, 0xffff0000, v4
	v_lshlrev_b32_e32 v58, 16, v4
	v_pk_add_f32 v[56:57], v[56:57], v[58:59] neg_lo:[0,1] neg_hi:[0,1]
	s_nop 0
	v_pk_fma_f32 v[56:57], v[50:51], v[56:57], v[58:59]
	s_and_saveexec_b64 s[48:49], s[6:7]
	s_cbranch_execz .LBB0_200
	s_and_saveexec_b64 s[40:41], s[4:5]
	s_xor_b64 s[50:51], exec, s[40:41]
	s_cbranch_execz .LBB0_197
	s_and_saveexec_b64 s[52:53], vcc

	v_mul_f32_e32 v55, 0xbfb8aa3b, v56
	v_mul_f32_e32 v56, 0xbfb8aa3b, v57
	v_exp_f32_e32 v55, v55
	v_exp_f32_e32 v56, v56
	v_add_f32_e32 v55, 1.0, v55
	v_add_f32_e32 v57, 1.0, v56
	v_rcp_f32_e32 v56, v55
	v_rcp_f32_e32 v57, v57

.LBB0_200:
	s_or_b64 exec, exec, s[48:49]
	ds_write_b64 v52, v[56:57] offset:10800
	v_and_b32_e32 v57, 0xffff0000, v5
	v_lshlrev_b32_e32 v56, 16, v5
	v_pk_add_f32 v[58:59], v[58:59], v[56:57] neg_lo:[0,1] neg_hi:[0,1]
	s_nop 0
	v_pk_fma_f32 v[58:59], v[50:51], v[58:59], v[56:57]
	s_and_saveexec_b64 s[48:49], s[6:7]
	s_cbranch_execz .LBB0_208
	s_and_saveexec_b64 s[40:41], s[4:5]
	s_xor_b64 s[50:51], exec, s[40:41]
	s_cbranch_execz .LBB0_205
	s_and_saveexec_b64 s[52:53], vcc

	v_mul_f32_e32 v55, 0xbfb8aa3b, v58
	v_mul_f32_e32 v58, 0xbfb8aa3b, v59
	v_exp_f32_e32 v55, v55
	v_exp_f32_e32 v58, v58
	v_add_f32_e32 v55, 1.0, v55
	v_add_f32_e32 v59, 1.0, v58
	v_rcp_f32_e32 v58, v55
	v_rcp_f32_e32 v59, v59

.LBB0_208:
	s_or_b64 exec, exec, s[48:49]
	ds_write_b64 v52, v[58:59] offset:14400
	v_and_b32_e32 v59, 0xffff0000, v6
	v_lshlrev_b32_e32 v58, 16, v6
	v_pk_add_f32 v[56:57], v[56:57], v[58:59] neg_lo:[0,1] neg_hi:[0,1]
	s_nop 0
	v_pk_fma_f32 v[56:57], v[50:51], v[56:57], v[58:59]
	s_and_saveexec_b64 s[48:49], s[6:7]
	s_cbranch_execz .LBB0_216
	s_and_saveexec_b64 s[40:41], s[4:5]
	s_xor_b64 s[50:51], exec, s[40:41]
	s_cbranch_execz .LBB0_213
	s_and_saveexec_b64 s[52:53], vcc

	v_mul_f32_e32 v55, 0xbfb8aa3b, v56
	v_mul_f32_e32 v56, 0xbfb8aa3b, v57
	v_exp_f32_e32 v55, v55
	v_exp_f32_e32 v56, v56
	v_add_f32_e32 v55, 1.0, v55
	v_add_f32_e32 v57, 1.0, v56
	v_rcp_f32_e32 v56, v55
	v_rcp_f32_e32 v57, v57

.LBB0_216:
	s_or_b64 exec, exec, s[48:49]
	ds_write_b64 v52, v[56:57] offset:18000
	v_and_b32_e32 v57, 0xffff0000, v7
	v_lshlrev_b32_e32 v56, 16, v7
	v_pk_add_f32 v[58:59], v[58:59], v[56:57] neg_lo:[0,1] neg_hi:[0,1]
	s_nop 0
	v_pk_fma_f32 v[58:59], v[50:51], v[58:59], v[56:57]
	s_and_saveexec_b64 s[48:49], s[6:7]
	s_cbranch_execz .LBB0_224
	s_and_saveexec_b64 s[40:41], s[4:5]
	s_xor_b64 s[50:51], exec, s[40:41]
	s_cbranch_execz .LBB0_221
	s_and_saveexec_b64 s[52:53], vcc

	v_mul_f32_e32 v55, 0xbfb8aa3b, v58
	v_mul_f32_e32 v58, 0xbfb8aa3b, v59
	v_exp_f32_e32 v55, v55
	v_exp_f32_e32 v58, v58
	v_add_f32_e32 v55, 1.0, v55
	v_add_f32_e32 v59, 1.0, v58
	v_rcp_f32_e32 v58, v55
	v_rcp_f32_e32 v59, v59

.LBB0_224:
	s_or_b64 exec, exec, s[48:49]
	ds_write_b64 v52, v[58:59] offset:21600
	v_and_b32_e32 v59, 0xffff0000, v8
	v_lshlrev_b32_e32 v58, 16, v8
	v_pk_add_f32 v[56:57], v[56:57], v[58:59] neg_lo:[0,1] neg_hi:[0,1]
	s_nop 0
	v_pk_fma_f32 v[56:57], v[50:51], v[56:57], v[58:59]
	s_and_saveexec_b64 s[48:49], s[6:7]
	s_cbranch_execz .LBB0_232
	s_and_saveexec_b64 s[40:41], s[4:5]
	s_xor_b64 s[50:51], exec, s[40:41]
	s_cbranch_execz .LBB0_229
	s_and_saveexec_b64 s[52:53], vcc

	v_mul_f32_e32 v55, 0xbfb8aa3b, v56
	v_mul_f32_e32 v56, 0xbfb8aa3b, v57
	v_exp_f32_e32 v55, v55
	v_exp_f32_e32 v56, v56
	v_add_f32_e32 v55, 1.0, v55
	v_add_f32_e32 v57, 1.0, v56
	v_rcp_f32_e32 v56, v55
	v_rcp_f32_e32 v57, v57

.LBB0_232:
	s_or_b64 exec, exec, s[48:49]
	ds_write_b64 v52, v[56:57] offset:25200
	v_and_b32_e32 v57, 0xffff0000, v9
	v_lshlrev_b32_e32 v56, 16, v9
	v_pk_add_f32 v[58:59], v[58:59], v[56:57] neg_lo:[0,1] neg_hi:[0,1]
	s_nop 0
	v_pk_fma_f32 v[58:59], v[50:51], v[58:59], v[56:57]
	s_and_saveexec_b64 s[48:49], s[6:7]
	s_cbranch_execz .LBB0_240
	s_and_saveexec_b64 s[40:41], s[4:5]
	s_xor_b64 s[50:51], exec, s[40:41]
	s_cbranch_execz .LBB0_237
	s_and_saveexec_b64 s[52:53], vcc

	v_mul_f32_e32 v55, 0xbfb8aa3b, v58
	v_mul_f32_e32 v58, 0xbfb8aa3b, v59
	v_exp_f32_e32 v55, v55
	v_exp_f32_e32 v58, v58
	v_add_f32_e32 v55, 1.0, v55
	v_add_f32_e32 v59, 1.0, v58
	v_rcp_f32_e32 v58, v55
	v_rcp_f32_e32 v59, v59

.LBB0_240:
	s_or_b64 exec, exec, s[48:49]
	ds_write_b64 v52, v[58:59] offset:28800
	v_and_b32_e32 v59, 0xffff0000, v10
	v_lshlrev_b32_e32 v58, 16, v10
	v_pk_add_f32 v[56:57], v[56:57], v[58:59] neg_lo:[0,1] neg_hi:[0,1]
	s_nop 0
	v_pk_fma_f32 v[56:57], v[50:51], v[56:57], v[58:59]
	s_and_saveexec_b64 s[48:49], s[6:7]
	s_cbranch_execz .LBB0_248
	s_and_saveexec_b64 s[40:41], s[4:5]
	s_xor_b64 s[50:51], exec, s[40:41]
	s_cbranch_execz .LBB0_245
	s_and_saveexec_b64 s[52:53], vcc

	v_mul_f32_e32 v55, 0xbfb8aa3b, v56
	v_mul_f32_e32 v56, 0xbfb8aa3b, v57
	v_exp_f32_e32 v55, v55
	v_exp_f32_e32 v56, v56
	v_add_f32_e32 v55, 1.0, v55
	v_add_f32_e32 v57, 1.0, v56
	v_rcp_f32_e32 v56, v55
	v_rcp_f32_e32 v57, v57

.LBB0_248:
	s_or_b64 exec, exec, s[48:49]
	ds_write_b64 v52, v[56:57] offset:32400
	v_and_b32_e32 v57, 0xffff0000, v11
	v_lshlrev_b32_e32 v56, 16, v11
	v_pk_add_f32 v[58:59], v[58:59], v[56:57] neg_lo:[0,1] neg_hi:[0,1]
	s_nop 0
	v_pk_fma_f32 v[58:59], v[50:51], v[58:59], v[56:57]
	s_and_saveexec_b64 s[48:49], s[6:7]
	s_cbranch_execz .LBB0_256
	s_and_saveexec_b64 s[40:41], s[4:5]
	s_xor_b64 s[50:51], exec, s[40:41]
	s_cbranch_execz .LBB0_253
	s_and_saveexec_b64 s[52:53], vcc

	v_mul_f32_e32 v55, 0xbfb8aa3b, v58
	v_mul_f32_e32 v58, 0xbfb8aa3b, v59
	v_exp_f32_e32 v55, v55
	v_exp_f32_e32 v58, v58
	v_add_f32_e32 v55, 1.0, v55
	v_add_f32_e32 v59, 1.0, v58
	v_rcp_f32_e32 v58, v55
	v_rcp_f32_e32 v59, v59

.LBB0_256:
	s_or_b64 exec, exec, s[48:49]
	ds_write_b64 v52, v[58:59] offset:36000
	v_and_b32_e32 v59, 0xffff0000, v12
	v_lshlrev_b32_e32 v58, 16, v12
	v_pk_add_f32 v[56:57], v[56:57], v[58:59] neg_lo:[0,1] neg_hi:[0,1]
	s_nop 0
	v_pk_fma_f32 v[56:57], v[50:51], v[56:57], v[58:59]
	s_and_saveexec_b64 s[48:49], s[6:7]
	s_cbranch_execz .LBB0_264
	s_and_saveexec_b64 s[40:41], s[4:5]
	s_xor_b64 s[50:51], exec, s[40:41]
	s_cbranch_execz .LBB0_261
	s_and_saveexec_b64 s[52:53], vcc

	v_mul_f32_e32 v55, 0xbfb8aa3b, v56
	v_mul_f32_e32 v56, 0xbfb8aa3b, v57
	v_exp_f32_e32 v55, v55
	v_exp_f32_e32 v56, v56
	v_add_f32_e32 v55, 1.0, v55
	v_add_f32_e32 v57, 1.0, v56
	v_rcp_f32_e32 v56, v55
	v_rcp_f32_e32 v57, v57

.LBB0_264:
	s_or_b64 exec, exec, s[48:49]
	ds_write_b64 v52, v[56:57] offset:39600
	v_and_b32_e32 v57, 0xffff0000, v13
	v_lshlrev_b32_e32 v56, 16, v13
	v_pk_add_f32 v[58:59], v[58:59], v[56:57] neg_lo:[0,1] neg_hi:[0,1]
	s_nop 0
	v_pk_fma_f32 v[58:59], v[50:51], v[58:59], v[56:57]
	s_and_saveexec_b64 s[48:49], s[6:7]
	s_cbranch_execz .LBB0_272
	s_and_saveexec_b64 s[40:41], s[4:5]
	s_xor_b64 s[50:51], exec, s[40:41]
	s_cbranch_execz .LBB0_269
	s_and_saveexec_b64 s[52:53], vcc

	v_mul_f32_e32 v55, 0xbfb8aa3b, v58
	v_mul_f32_e32 v58, 0xbfb8aa3b, v59
	v_exp_f32_e32 v55, v55
	v_exp_f32_e32 v58, v58
	v_add_f32_e32 v55, 1.0, v55
	v_add_f32_e32 v59, 1.0, v58
	v_rcp_f32_e32 v58, v55
	v_rcp_f32_e32 v59, v59

.LBB0_272:
	s_or_b64 exec, exec, s[48:49]
	ds_write_b64 v52, v[58:59] offset:43200
	v_and_b32_e32 v59, 0xffff0000, v14
	v_lshlrev_b32_e32 v58, 16, v14
	v_pk_add_f32 v[56:57], v[56:57], v[58:59] neg_lo:[0,1] neg_hi:[0,1]
	s_nop 0
	v_pk_fma_f32 v[56:57], v[50:51], v[56:57], v[58:59]
	s_and_saveexec_b64 s[48:49], s[6:7]
	s_cbranch_execz .LBB0_280
	s_and_saveexec_b64 s[40:41], s[4:5]
	s_xor_b64 s[50:51], exec, s[40:41]
	s_cbranch_execz .LBB0_277
	s_and_saveexec_b64 s[52:53], vcc

	v_mul_f32_e32 v55, 0xbfb8aa3b, v56
	v_mul_f32_e32 v56, 0xbfb8aa3b, v57
	v_exp_f32_e32 v55, v55
	v_exp_f32_e32 v56, v56
	v_add_f32_e32 v55, 1.0, v55
	v_add_f32_e32 v57, 1.0, v56
	v_rcp_f32_e32 v56, v55
	v_rcp_f32_e32 v57, v57

.LBB0_280:
	s_or_b64 exec, exec, s[48:49]
	ds_write_b64 v52, v[56:57] offset:46800
	v_and_b32_e32 v57, 0xffff0000, v15
	v_lshlrev_b32_e32 v56, 16, v15
	v_pk_add_f32 v[58:59], v[58:59], v[56:57] neg_lo:[0,1] neg_hi:[0,1]
	s_nop 0
	v_pk_fma_f32 v[58:59], v[50:51], v[58:59], v[56:57]
	s_and_saveexec_b64 s[48:49], s[6:7]
	s_cbranch_execz .LBB0_288
	s_and_saveexec_b64 s[40:41], s[4:5]
	s_xor_b64 s[50:51], exec, s[40:41]
	s_cbranch_execz .LBB0_285
	s_and_saveexec_b64 s[52:53], vcc

	v_mul_f32_e32 v55, 0xbfb8aa3b, v58
	v_mul_f32_e32 v58, 0xbfb8aa3b, v59
	v_exp_f32_e32 v55, v55
	v_exp_f32_e32 v58, v58
	v_add_f32_e32 v55, 1.0, v55
	v_add_f32_e32 v59, 1.0, v58
	v_rcp_f32_e32 v58, v55
	v_rcp_f32_e32 v59, v59

.LBB0_288:
	s_or_b64 exec, exec, s[48:49]
	ds_write_b64 v52, v[58:59] offset:50400
	v_and_b32_e32 v59, 0xffff0000, v16
	v_lshlrev_b32_e32 v58, 16, v16
	v_pk_add_f32 v[56:57], v[56:57], v[58:59] neg_lo:[0,1] neg_hi:[0,1]
	s_nop 0
	v_pk_fma_f32 v[56:57], v[50:51], v[56:57], v[58:59]
	s_and_saveexec_b64 s[48:49], s[6:7]
	s_cbranch_execz .LBB0_296
	s_and_saveexec_b64 s[6:7], s[4:5]
	s_xor_b64 s[4:5], exec, s[6:7]
	s_cbranch_execz .LBB0_293
	s_and_saveexec_b64 s[6:7], vcc

	v_mul_f32_e32 v55, 0xbfb8aa3b, v56
	v_mul_f32_e32 v56, 0xbfb8aa3b, v57
	v_exp_f32_e32 v55, v55
	v_exp_f32_e32 v56, v56
	v_add_f32_e32 v55, 1.0, v55
	v_add_f32_e32 v57, 1.0, v56
	v_rcp_f32_e32 v56, v55
	v_rcp_f32_e32 v57, v57

.LBB0_300:
	v_lshlrev_b32_e32 v56, 1, v54
	s_lshl_b64 s[4:5], s[10:11], 11
	s_add_u32 s4, s8, s4
	s_addc_u32 s5, s9, s5
	global_load_dword v1, v56, s[4:5]
	global_load_dword v2, v56, s[4:5] offset:2048
	s_add_u32 s4, s4, 0x1000
	s_addc_u32 s5, s5, 0
	global_load_dword v3, v56, s[4:5]
	global_load_dword v4, v56, s[4:5] offset:2048
	s_add_u32 s4, s4, 0x1000
	s_addc_u32 s5, s5, 0
	global_load_dword v5, v56, s[4:5]
	global_load_dword v6, v56, s[4:5] offset:2048
	s_add_u32 s4, s4, 0x1000
	s_addc_u32 s5, s5, 0
	global_load_dword v7, v56, s[4:5]
	global_load_dword v8, v56, s[4:5] offset:2048
	s_add_u32 s4, s4, 0x1000
	s_addc_u32 s5, s5, 0
	global_load_dword v9, v56, s[4:5]
	global_load_dword v10, v56, s[4:5] offset:2048
	s_add_u32 s4, s4, 0x1000
	s_addc_u32 s5, s5, 0
	global_load_dword v11, v56, s[4:5]
	global_load_dword v12, v56, s[4:5] offset:2048
	s_add_u32 s4, s4, 0x1000
	s_addc_u32 s5, s5, 0
	global_load_dword v13, v56, s[4:5]
	global_load_dword v14, v56, s[4:5] offset:2048
	s_add_u32 s4, s4, 0x1000
	s_addc_u32 s5, s5, 0
	global_load_dword v15, v56, s[4:5]
	global_load_dword v16, v56, s[4:5] offset:2048
	s_or_b32 s10, s10, 15
.LBB0_301:
	s_or_b64 exec, exec, s[44:45]
	v_and_b32_e32 v52, 15, v111
	v_bfe_u32 v55, v111, 4, 2
	v_mul_u32_u24_e32 v56, 0xe10, v52
	v_lshlrev_b32_e32 v57, 5, v55
	v_add3_u32 v80, 0, v56, v57
	s_waitcnt lgkmcnt(0)
	s_barrier
	ds_read_b128 v[56:59], v80 offset:3072
	ds_read_b128 v[60:63], v80 offset:3088
	s_waitcnt lgkmcnt(1)
	v_cvt_pk_bf16_f32 v56, v56, v57
	v_cvt_pk_bf16_f32 v57, v58, v59
	s_waitcnt lgkmcnt(0)
	v_cvt_pk_bf16_f32 v58, v60, v61
	v_cvt_pk_bf16_f32 v59, v62, v63
	ds_read_b128 v[60:63], v80 offset:3200
	ds_read_b128 v[64:67], v80 offset:3216
	s_waitcnt lgkmcnt(1)
	v_cvt_pk_bf16_f32 v60, v60, v61
	v_cvt_pk_bf16_f32 v61, v62, v63
	s_waitcnt lgkmcnt(0)
	v_cvt_pk_bf16_f32 v62, v64, v65
	v_cvt_pk_bf16_f32 v63, v66, v67
	ds_read_b128 v[64:67], v80 offset:3328
	ds_read_b128 v[68:71], v80 offset:3344
	s_waitcnt lgkmcnt(1)
	v_cvt_pk_bf16_f32 v64, v64, v65
	v_cvt_pk_bf16_f32 v65, v66, v67
	s_waitcnt lgkmcnt(0)
	v_cvt_pk_bf16_f32 v66, v68, v69
	v_cvt_pk_bf16_f32 v67, v70, v71
	v_mfma_f32_16x16x32_bf16 v[72:75], v[56:59], v[18:21], 0
	ds_read_b128 v[68:71], v80 offset:3456
	ds_read_b128 v[80:83], v80 offset:3472
	v_lshl_add_u32 v55, v55, 12, 0
	v_mfma_f32_16x16x32_bf16 v[84:87], v[64:67], v[26:29], 0
	v_and_b32_e32 v54, 0xffffff80, v54
	v_lshlrev_b32_e32 v52, 2, v52
	s_waitcnt lgkmcnt(1)
	v_cvt_pk_bf16_f32 v68, v68, v69
	v_mfma_f32_16x16x32_bf16 v[64:67], v[64:67], v[42:45], 0
	v_cvt_pk_bf16_f32 v69, v70, v71
	s_waitcnt lgkmcnt(0)
	v_cvt_pk_bf16_f32 v70, v80, v81
	v_cvt_pk_bf16_f32 v71, v82, v83
	v_mfma_f32_16x16x32_bf16 v[56:59], v[56:59], v[34:37], 0
	v_add3_u32 v52, v55, v54, v52
	v_add_u32_e32 v54, 0xe900, v52
	v_add_u32_e32 v55, 0xe800, v52
	v_mfma_f32_16x16x32_bf16 v[76:79], v[60:63], v[22:25], 0
	s_ashr_i32 s37, s36, 31
	s_nop 2
	ds_write2_b32 v55, v72, v56 offset0:64 offset1:80
	v_add_u32_e32 v55, 0x4000, v54
	v_mfma_f32_16x16x32_bf16 v[60:63], v[60:63], v[38:41], 0
	v_lshlrev_b32_sdwa v72, v17, v111 dst_sel:DWORD dst_unused:UNUSED_PAD src0_sel:DWORD src1_sel:BYTE_0
	v_and_b32_e32 v102, 63, v111
	v_mfma_f32_16x16x32_bf16 v[80:83], v[68:71], v[30:33], v[84:87]
	v_mfma_f32_16x16x32_bf16 v[64:67], v[68:71], v[46:49], v[64:67]
	s_nop 3
	ds_write2_b32 v55, v76, v60 offset1:16
	v_add_u32_e32 v55, 0x8000, v54
	v_ashrrev_i32_e32 v70, 8, v111
	v_lshlrev_b32_e32 v118, 3, v70
	v_ashrrev_i32_e32 v119, 31, v118
	ds_write2_b32 v55, v80, v64 offset1:16
	v_add_u32_e32 v55, 0xc000, v54
	ds_write2_b32 v55, v53, v53 offset1:16
	v_add_u32_e32 v55, 0xec00, v52
	ds_write2_b32 v55, v73, v57 offset0:64 offset1:80
	v_add_u32_e32 v55, 0x4400, v54
	ds_write2_b32 v55, v77, v61 offset1:16
	v_add_u32_e32 v55, 0x8400, v54
	ds_write2_b32 v55, v81, v65 offset1:16
	v_add_u32_e32 v55, 0xc400, v54
	ds_write2_b32 v55, v53, v53 offset1:16
	v_add_u32_e32 v55, 0xf000, v52
	v_add_u32_e32 v52, 0xf400, v52
	ds_write2_b32 v52, v75, v59 offset0:64 offset1:80
	v_add_u32_e32 v52, 0x4c00, v54
	ds_write2_b32 v52, v79, v63 offset1:16
	v_add_u32_e32 v52, 0x8c00, v54
	ds_write2_b32 v52, v83, v67 offset1:16
	v_add_u32_e32 v52, 0xcc00, v54
	ds_write2_b32 v55, v74, v58 offset0:64 offset1:80
	v_add_u32_e32 v55, 0x4800, v54
	ds_write2_b32 v52, v53, v53 offset1:16
	v_lshlrev_b32_e32 v52, 13, v70
	ds_write2_b32 v55, v78, v62 offset1:16
	v_add_u32_e32 v55, 0x8800, v54
	v_add3_u32 v52, 0, v52, v72
	ds_write2_b32 v55, v82, v66 offset1:16
	v_add_u32_e32 v55, 0xc800, v54
	v_add_u32_e32 v54, 0xe900, v52
	ds_write2_b32 v55, v53, v53 offset1:16
	s_waitcnt lgkmcnt(0)
	s_barrier
	ds_read2st64_b32 v[90:91], v52 offset0:233 offset1:237
	ds_read2st64_b32 v[62:63], v54 offset0:64 offset1:68
	ds_read2st64_b32 v[84:85], v54 offset0:128 offset1:132
	ds_read2st64_b32 v[74:75], v52 offset0:241 offset1:245
	ds_read2st64_b32 v[66:67], v54 offset0:72 offset1:76
	ds_read2st64_b32 v[64:65], v54 offset0:136 offset1:140
	ds_read2st64_b32 v[60:61], v52 offset0:249 offset1:253
	ds_read2st64_b32 v[68:69], v54 offset0:80 offset1:84
	ds_read2st64_b32 v[58:59], v54 offset0:144 offset1:148
	ds_read2st64_b32 v[56:57], v54 offset0:24 offset1:28
	ds_read2st64_b32 v[124:125], v54 offset0:88 offset1:92
	ds_read2st64_b32 v[54:55], v54 offset0:152 offset1:156
	s_waitcnt vmcnt(4) lgkmcnt(11)
	v_add_f32_e32 v71, v104, v90
	v_mul_f32_e32 v71, 0xbfb8aa3b, v71
	v_exp_f32_e32 v71, v71
	v_lshlrev_b32_sdwa v52, v109, v111 dst_sel:DWORD dst_unused:UNUSED_PAD src0_sel:DWORD src1_sel:BYTE_0
	v_lshl_add_u64 v[134:135], s[20:21], 0, v[52:53]
	s_waitcnt vmcnt(3) lgkmcnt(10)
	v_add_f32_e32 v62, v105, v62
	v_add_f32_e32 v52, 1.0, v71
	v_rcp_f32_e32 v52, v52
	v_mul_f32_e32 v62, 0xbfb8aa3b, v62
	v_exp_f32_e32 v62, v62
	v_mul_i32_i24_e32 v70, 0x7080, v70
	v_mul_f32_e32 v52, 0xbf1b4598, v52
	v_mul_f32_e32 v52, 0x3fb8aa3b, v52
	v_exp_f32_e32 v120, v52
	v_add_f32_e32 v52, 1.0, v62
	v_add3_u32 v70, 0, v70, v72
	v_rcp_f32_e32 v52, v52
	v_lshl_add_u64 v[96:97], v[118:119], 0, s[36:37]
	ds_read2st64_b32 v[100:101], v70 offset1:4
	ds_read_b32 v90, v70 offset:2048
	v_lshlrev_b64 v[70:71], 9, v[96:97]
	v_lshl_add_u64 v[70:71], v[134:135], 0, v[70:71]
	s_waitcnt lgkmcnt(0)
	v_cvt_pk_bf16_f32 v62, v90, v53
	global_store_short v[70:71], v62, off
	v_add_f32_e32 v62, -1.0, v52
	s_waitcnt vmcnt(2)
	v_fma_f32 v62, v107, v62, 1.0
	v_or_b32_e32 v70, 1, v118
	v_mul_f32_e32 v132, v62, v101
	v_mul_lo_u32 v62, v70, s61
	v_add3_u32 v123, 0, v62, v72
	v_add_f32_e32 v62, v105, v63
	v_mul_f32_e32 v62, 0xbfb8aa3b, v62
	v_exp_f32_e32 v62, v62
	v_ashrrev_i32_e32 v71, 31, v70
	v_lshl_add_u64 v[94:95], v[70:71], 0, s[36:37]
	ds_read2st64_b32 v[98:99], v123 offset1:4
	v_add_f32_e32 v62, 1.0, v62
	v_rcp_f32_e32 v127, v62
	v_lshlrev_b64 v[62:63], 9, v[94:95]
	v_lshl_add_u64 v[62:63], v[134:135], 0, v[62:63]
	ds_read_b32 v122, v123 offset:2048
	s_waitcnt lgkmcnt(0)
	v_cvt_pk_bf16_f32 v70, v122, v53
	global_store_short v[62:63], v70, off
	v_add_f32_e32 v62, -1.0, v127
	v_fma_f32 v62, v107, v62, 1.0
	v_mul_f32_e32 v126, v62, v99
	v_or_b32_e32 v62, 2, v118
	v_ashrrev_i32_e32 v63, 31, v62
	v_lshl_add_u64 v[86:87], v[62:63], 0, s[36:37]
	v_add_f32_e32 v62, v105, v66
	v_mul_f32_e32 v62, 0xbfb8aa3b, v62
	v_exp_f32_e32 v62, v62
	v_add_u32_e32 v63, 16, v123
	ds_read2st64_b32 v[92:93], v63 offset0:14 offset1:18
	ds_read_b32 v117, v123 offset:5648
	v_add_f32_e32 v62, 1.0, v62
	v_rcp_f32_e32 v137, v62
	v_lshlrev_b64 v[62:63], 9, v[86:87]
	v_lshl_add_u64 v[62:63], v[134:135], 0, v[62:63]
	s_waitcnt lgkmcnt(0)
	v_cvt_pk_bf16_f32 v66, v117, v53
	global_store_short v[62:63], v66, off
	v_add_f32_e32 v62, -1.0, v137
	v_fma_f32 v62, v107, v62, 1.0
	v_mul_f32_e32 v121, v62, v93
	v_or_b32_e32 v62, 3, v118
	v_ashrrev_i32_e32 v63, 31, v62
	v_lshl_add_u64 v[80:81], v[62:63], 0, s[36:37]
	v_add_f32_e32 v62, v105, v67
	v_mul_f32_e32 v62, 0xbfb8aa3b, v62
	v_exp_f32_e32 v62, v62
	v_add_u32_e32 v63, 32, v123
	ds_read2st64_b32 v[88:89], v63 offset0:28 offset1:32
	ds_read_b32 v114, v123 offset:9248
	v_add_f32_e32 v62, 1.0, v62
	v_rcp_f32_e32 v119, v62
	v_lshlrev_b64 v[62:63], 9, v[80:81]
	v_lshl_add_u64 v[62:63], v[134:135], 0, v[62:63]
	s_waitcnt lgkmcnt(0)
	v_cvt_pk_bf16_f32 v66, v114, v53
	global_store_short v[62:63], v66, off
	v_add_f32_e32 v62, -1.0, v119
	v_fma_f32 v62, v107, v62, 1.0
	v_mul_f32_e32 v116, v62, v89
	v_or_b32_e32 v62, 4, v118
	v_ashrrev_i32_e32 v63, 31, v62
	v_lshl_add_u64 v[76:77], v[62:63], 0, s[36:37]
	v_add_f32_e32 v62, v105, v68
	v_mul_f32_e32 v62, 0xbfb8aa3b, v62
	v_exp_f32_e32 v62, v62
	v_add_u32_e32 v63, 48, v123
	ds_read2st64_b32 v[82:83], v63 offset0:42 offset1:46
	v_mul_f32_e32 v103, v106, v101
	v_add_f32_e32 v62, 1.0, v62
	v_rcp_f32_e32 v142, v62
	v_lshlrev_b64 v[62:63], 9, v[76:77]
	v_lshl_add_u64 v[62:63], v[134:135], 0, v[62:63]
	ds_read_b32 v101, v123 offset:12848
	s_waitcnt lgkmcnt(0)
	v_cvt_pk_bf16_f32 v66, v101, v53
	global_store_short v[62:63], v66, off
	v_add_f32_e32 v62, -1.0, v142
	v_fma_f32 v62, v107, v62, 1.0
	v_mul_f32_e32 v113, v62, v83
	v_or_b32_e32 v62, 5, v118
	v_ashrrev_i32_e32 v63, 31, v62
	v_lshl_add_u64 v[70:71], v[62:63], 0, s[36:37]
	v_add_f32_e32 v62, v105, v69
	v_mul_f32_e32 v62, 0xbfb8aa3b, v62
	v_exp_f32_e32 v62, v62
	v_add_u32_e32 v63, 64, v123
	ds_read2st64_b32 v[78:79], v63 offset0:56 offset1:60
	v_mul_f32_e32 v138, v106, v93
	v_add_f32_e32 v62, 1.0, v62
	v_rcp_f32_e32 v112, v62
	v_lshlrev_b64 v[62:63], 9, v[70:71]
	v_lshl_add_u64 v[62:63], v[134:135], 0, v[62:63]
	ds_read_b32 v93, v123 offset:16448
	s_waitcnt lgkmcnt(0)
	v_cvt_pk_bf16_f32 v66, v93, v53
	global_store_short v[62:63], v66, off
	v_add_f32_e32 v62, -1.0, v112
	v_fma_f32 v62, v107, v62, 1.0
	v_mul_f32_e32 v133, v106, v99
	v_mul_f32_e32 v99, v62, v79
	v_or_b32_e32 v62, 6, v118
	v_ashrrev_i32_e32 v63, 31, v62
	v_lshl_add_u64 v[66:67], v[62:63], 0, s[36:37]
	v_add_f32_e32 v62, v105, v124
	v_mul_f32_e32 v62, 0xbfb8aa3b, v62
	v_exp_f32_e32 v62, v62
	v_add_u32_e32 v63, 0x50, v123
	ds_read2st64_b32 v[72:73], v63 offset0:70 offset1:74
	v_mul_f32_e32 v145, v106, v79
	v_add_f32_e32 v62, 1.0, v62
	v_rcp_f32_e32 v148, v62
	v_lshlrev_b64 v[62:63], 9, v[66:67]
	v_lshl_add_u64 v[62:63], v[134:135], 0, v[62:63]
	ds_read_b32 v79, v123 offset:20048
	s_waitcnt lgkmcnt(0)
	v_cvt_pk_bf16_f32 v68, v79, v53
	global_store_short v[62:63], v68, off
	v_add_f32_e32 v62, -1.0, v148
	v_fma_f32 v62, v107, v62, 1.0
	v_mul_f32_e32 v140, v106, v89
	v_mul_f32_e32 v89, v62, v73
	v_or_b32_e32 v62, 7, v118
	v_ashrrev_i32_e32 v63, 31, v62
	v_lshl_add_u64 v[62:63], v[62:63], 0, s[36:37]
	v_add_f32_e32 v68, v105, v125
	v_mul_f32_e32 v68, 0xbfb8aa3b, v68
	v_lshlrev_b64 v[124:125], 9, v[62:63]
	v_mul_f32_e32 v136, v133, v133
	v_mul_f32_e32 v143, v106, v83
	v_exp_f32_e32 v83, v68
	v_add_u32_e32 v68, 0x60, v123
	v_lshl_add_u64 v[124:125], v[134:135], 0, v[124:125]
	v_mul_f32_e32 v149, v106, v73
	ds_read_b32 v73, v123 offset:23648
	ds_read2st64_b32 v[68:69], v68 offset0:84 offset1:88
	s_waitcnt lgkmcnt(1)
	v_cvt_pk_bf16_f32 v118, v73, v53
	global_store_short v[124:125], v118, off
	v_and_b32_e32 v125, 64, v110
	v_mov_b32_dpp v135, v136 quad_perm:[1,0,3,2] row_mask:0xf bank_mask:0xf bound_ctrl:1
	v_xor_b32_e32 v124, 16, v110
	v_add_u32_e32 v125, 64, v125
	v_fmac_f32_e32 v135, v133, v133
	v_cmp_lt_i32_e32 vcc, v124, v125
	v_mul_f32_e32 v115, v103, v103
	v_add_f32_dpp v135, v135, v135 quad_perm:[2,3,0,1] row_mask:0xf bank_mask:0xf bound_ctrl:1
	v_cndmask_b32_e32 v124, v110, v124, vcc
	v_lshlrev_b32_e32 v151, 2, v124
	v_add_f32_dpp v135, v135, v135 row_half_mirror row_mask:0xf bank_mask:0xf bound_ctrl:1
	v_mul_f32_e32 v139, v138, v138
	v_xor_b32_e32 v124, 32, v110
	v_add_f32_dpp v135, v135, v135 row_mirror row_mask:0xf bank_mask:0xf bound_ctrl:1
	ds_bpermute_b32 v136, v151, v135
	v_mov_b32_dpp v115, v115 quad_perm:[1,0,3,2] row_mask:0xf bank_mask:0xf bound_ctrl:1
	v_cmp_lt_i32_e32 vcc, v124, v125
	v_fmac_f32_e32 v115, v103, v103
	v_add_f32_e32 v83, 1.0, v83
	s_waitcnt lgkmcnt(0)
	v_add_f32_e32 v125, v135, v136
	v_mov_b32_dpp v135, v139 quad_perm:[1,0,3,2] row_mask:0xf bank_mask:0xf bound_ctrl:1
	v_fmac_f32_e32 v135, v138, v138
	v_add_f32_dpp v115, v115, v115 quad_perm:[2,3,0,1] row_mask:0xf bank_mask:0xf bound_ctrl:1
	v_mul_f32_e32 v141, v140, v140
	v_add_f32_dpp v135, v135, v135 quad_perm:[2,3,0,1] row_mask:0xf bank_mask:0xf bound_ctrl:1
	v_add_f32_dpp v115, v115, v115 row_half_mirror row_mask:0xf bank_mask:0xf bound_ctrl:1
	v_rcp_f32_e32 v83, v83
	v_add_f32_dpp v135, v135, v135 row_half_mirror row_mask:0xf bank_mask:0xf bound_ctrl:1
	v_add_f32_dpp v115, v115, v115 row_mirror row_mask:0xf bank_mask:0xf bound_ctrl:1
	ds_bpermute_b32 v134, v151, v115
	v_add_f32_dpp v135, v135, v135 row_mirror row_mask:0xf bank_mask:0xf bound_ctrl:1
	ds_bpermute_b32 v136, v151, v135
	v_mov_b32_dpp v139, v141 quad_perm:[1,0,3,2] row_mask:0xf bank_mask:0xf bound_ctrl:1
	v_fmac_f32_e32 v139, v140, v140
	v_add_f32_e32 v123, -1.0, v83
	v_mul_f32_e32 v144, v143, v143
	v_add_f32_dpp v139, v139, v139 quad_perm:[2,3,0,1] row_mask:0xf bank_mask:0xf bound_ctrl:1
	v_mul_f32_e32 v118, v106, v69
	v_fma_f32 v123, v107, v123, 1.0
	v_add_f32_dpp v139, v139, v139 row_half_mirror row_mask:0xf bank_mask:0xf bound_ctrl:1
	v_cndmask_b32_e32 v124, v110, v124, vcc
	v_mul_f32_e32 v69, v123, v69
	v_add_f32_dpp v139, v139, v139 row_mirror row_mask:0xf bank_mask:0xf bound_ctrl:1
	v_mul_f32_e32 v123, v118, v118
	v_lshlrev_b32_e32 v173, 2, v124
	s_waitcnt lgkmcnt(1)
	v_add_f32_e32 v115, v115, v134
	ds_bpermute_b32 v141, v151, v139
	v_mov_b32_dpp v144, v144 quad_perm:[1,0,3,2] row_mask:0xf bank_mask:0xf bound_ctrl:1
	s_waitcnt lgkmcnt(1)
	v_add_f32_e32 v135, v135, v136
	ds_bpermute_b32 v124, v173, v115
	ds_bpermute_b32 v134, v173, v125
	v_fmac_f32_e32 v144, v143, v143
	ds_bpermute_b32 v136, v173, v135
	v_mov_b32_dpp v123, v123 quad_perm:[1,0,3,2] row_mask:0xf bank_mask:0xf bound_ctrl:1
	v_add_f32_dpp v144, v144, v144 quad_perm:[2,3,0,1] row_mask:0xf bank_mask:0xf bound_ctrl:1
	v_fmac_f32_e32 v123, v118, v118
	v_mul_f32_e32 v146, v145, v145
	v_add_f32_dpp v144, v144, v144 row_half_mirror row_mask:0xf bank_mask:0xf bound_ctrl:1
	v_add_f32_dpp v123, v123, v123 quad_perm:[2,3,0,1] row_mask:0xf bank_mask:0xf bound_ctrl:1
	s_waitcnt lgkmcnt(3)
	v_add_f32_e32 v139, v139, v141
	v_add_f32_dpp v144, v144, v144 row_mirror row_mask:0xf bank_mask:0xf bound_ctrl:1
	v_add_f32_dpp v123, v123, v123 row_half_mirror row_mask:0xf bank_mask:0xf bound_ctrl:1
	ds_bpermute_b32 v150, v151, v144
	ds_bpermute_b32 v141, v173, v139
	v_add_f32_dpp v123, v123, v123 row_mirror row_mask:0xf bank_mask:0xf bound_ctrl:1
	s_waitcnt lgkmcnt(4)
	v_add_f32_e32 v115, v115, v124
	s_waitcnt lgkmcnt(3)
	v_add_f32_e32 v124, v125, v134
	s_waitcnt lgkmcnt(2)
	v_add_f32_e32 v125, v135, v136
	v_mov_b32_dpp v136, v146 quad_perm:[1,0,3,2] row_mask:0xf bank_mask:0xf bound_ctrl:1
	ds_bpermute_b32 v146, v151, v123
	v_mul_f32_e32 v147, v149, v149
	s_waitcnt lgkmcnt(2)
	v_add_f32_e32 v144, v144, v150
	ds_bpermute_b32 v150, v173, v144
	s_waitcnt lgkmcnt(2)
	v_add_f32_e32 v134, v139, v141
	v_mov_b32_dpp v141, v147 quad_perm:[1,0,3,2] row_mask:0xf bank_mask:0xf bound_ctrl:1
	s_waitcnt lgkmcnt(1)
	v_add_f32_e32 v123, v123, v146
	v_fmac_f32_e32 v136, v145, v145
	v_fmac_f32_e32 v141, v149, v149
	ds_bpermute_b32 v146, v173, v123
	v_add_f32_dpp v136, v136, v136 quad_perm:[2,3,0,1] row_mask:0xf bank_mask:0xf bound_ctrl:1
	v_add_f32_dpp v141, v141, v141 quad_perm:[2,3,0,1] row_mask:0xf bank_mask:0xf bound_ctrl:1
	v_max_f32_e32 v115, 0x179abe15, v115
	v_add_f32_dpp v136, v136, v136 row_half_mirror row_mask:0xf bank_mask:0xf bound_ctrl:1
	v_add_f32_dpp v141, v141, v141 row_half_mirror row_mask:0xf bank_mask:0xf bound_ctrl:1
	s_waitcnt lgkmcnt(1)
	v_add_f32_e32 v135, v144, v150
	v_add_f32_dpp v136, v136, v136 row_mirror row_mask:0xf bank_mask:0xf bound_ctrl:1
	v_add_f32_dpp v141, v141, v141 row_mirror row_mask:0xf bank_mask:0xf bound_ctrl:1
	ds_bpermute_b32 v139, v151, v136
	ds_bpermute_b32 v144, v151, v141
	v_rsq_f32_e32 v115, v115
	s_waitcnt lgkmcnt(2)
	v_add_f32_e32 v123, v123, v146
	v_max_f32_e32 v123, 0x179abe15, v123
	v_rsq_f32_e32 v123, v123
	v_mul_f32_e32 v157, v103, v115
	s_waitcnt lgkmcnt(1)
	v_add_f32_e32 v136, v136, v139
	s_waitcnt lgkmcnt(0)
	v_add_f32_e32 v141, v141, v144
	v_mul_f32_e32 v178, v52, v157
	v_mul_f32_e32 v52, v100, v132
	v_max_f32_e32 v103, 0x179abe15, v124
	ds_bpermute_b32 v139, v173, v136
	ds_bpermute_b32 v144, v173, v141
	v_rsq_f32_e32 v103, v103
	s_waitcnt vmcnt(8)
	v_mul_f32_e32 v124, v108, v52
	v_mul_f32_e32 v118, v118, v123
	v_max_f32_e32 v115, 0x179abe15, v125
	v_mov_b32_dpp v123, v124 quad_perm:[1,0,3,2] row_mask:0xf bank_mask:0xf bound_ctrl:1
	v_fmac_f32_e32 v123, v108, v52
	v_rsq_f32_e32 v115, v115
	v_mul_f32_e32 v158, v133, v103
	v_add_f32_dpp v52, v123, v123 quad_perm:[2,3,0,1] row_mask:0xf bank_mask:0xf bound_ctrl:1
	v_mul_f32_e32 v103, v98, v126
	s_waitcnt lgkmcnt(1)
	v_add_f32_e32 v136, v136, v139
	v_add_f32_dpp v52, v52, v52 row_half_mirror row_mask:0xf bank_mask:0xf bound_ctrl:1
	s_waitcnt lgkmcnt(0)
	v_add_f32_e32 v139, v141, v144
	v_mul_f32_e32 v141, v108, v103
	v_add_f32_dpp v52, v52, v52 row_mirror row_mask:0xf bank_mask:0xf bound_ctrl:1
	ds_bpermute_b32 v123, v151, v52
	v_mov_b32_dpp v124, v141 quad_perm:[1,0,3,2] row_mask:0xf bank_mask:0xf bound_ctrl:1
	v_fmac_f32_e32 v124, v108, v103
	v_mul_f32_e32 v144, v138, v115
	v_mul_f32_e32 v150, v137, v144
	v_add_f32_dpp v103, v124, v124 quad_perm:[2,3,0,1] row_mask:0xf bank_mask:0xf bound_ctrl:1
	v_mul_f32_e32 v137, v92, v121
	v_mul_f32_e32 v146, v108, v137
	v_add_f32_dpp v103, v103, v103 row_half_mirror row_mask:0xf bank_mask:0xf bound_ctrl:1
	s_waitcnt lgkmcnt(0)
	v_add_f32_e32 v167, v52, v123
	v_mov_b32_dpp v52, v146 quad_perm:[1,0,3,2] row_mask:0xf bank_mask:0xf bound_ctrl:1
	v_add_f32_dpp v103, v103, v103 row_mirror row_mask:0xf bank_mask:0xf bound_ctrl:1
	ds_bpermute_b32 v124, v151, v103
	v_fmac_f32_e32 v52, v108, v137
	v_max_f32_e32 v125, 0x179abe15, v135
	v_max_f32_e32 v115, 0x179abe15, v134
	v_add_f32_dpp v52, v52, v52 quad_perm:[2,3,0,1] row_mask:0xf bank_mask:0xf bound_ctrl:1
	v_rsq_f32_e32 v125, v125
	v_rsq_f32_e32 v115, v115
	v_add_f32_dpp v52, v52, v52 row_half_mirror row_mask:0xf bank_mask:0xf bound_ctrl:1
	s_waitcnt lgkmcnt(0)
	v_add_f32_e32 v161, v103, v124
	v_mul_f32_e32 v135, v88, v116
	v_add_f32_dpp v52, v52, v52 row_mirror row_mask:0xf bank_mask:0xf bound_ctrl:1
	ds_bpermute_b32 v103, v151, v52
	v_mul_f32_e32 v133, v143, v125
	v_mul_f32_e32 v147, v140, v115
	v_mul_f32_e32 v140, v108, v135
	v_mul_f32_e32 v138, v142, v133
	v_mul_f32_e32 v142, v82, v113
	v_max_f32_e32 v125, 0x179abe15, v139
	v_mul_f32_e32 v139, v78, v99
	v_max_f32_e32 v115, 0x179abe15, v136
	v_mul_f32_e32 v136, v108, v142
	v_mul_f32_e32 v143, v108, v139
	v_mov_b32_dpp v123, v140 quad_perm:[1,0,3,2] row_mask:0xf bank_mask:0xf bound_ctrl:1
	v_fmac_f32_e32 v123, v108, v135
	v_mov_b32_dpp v135, v136 quad_perm:[1,0,3,2] row_mask:0xf bank_mask:0xf bound_ctrl:1
	s_waitcnt lgkmcnt(0)
	v_add_f32_e32 v159, v52, v103
	v_mov_b32_dpp v52, v143 quad_perm:[1,0,3,2] row_mask:0xf bank_mask:0xf bound_ctrl:1
	v_fmac_f32_e32 v135, v108, v142
	v_fmac_f32_e32 v52, v108, v139
	v_add_f32_dpp v123, v123, v123 quad_perm:[2,3,0,1] row_mask:0xf bank_mask:0xf bound_ctrl:1
	v_add_f32_dpp v135, v135, v135 quad_perm:[2,3,0,1] row_mask:0xf bank_mask:0xf bound_ctrl:1
	v_add_f32_dpp v52, v52, v52 quad_perm:[2,3,0,1] row_mask:0xf bank_mask:0xf bound_ctrl:1
	v_add_f32_dpp v123, v123, v123 row_half_mirror row_mask:0xf bank_mask:0xf bound_ctrl:1
	v_add_f32_dpp v135, v135, v135 row_half_mirror row_mask:0xf bank_mask:0xf bound_ctrl:1
	v_add_f32_dpp v52, v52, v52 row_half_mirror row_mask:0xf bank_mask:0xf bound_ctrl:1
	v_add_f32_dpp v123, v123, v123 row_mirror row_mask:0xf bank_mask:0xf bound_ctrl:1
	v_add_f32_dpp v135, v135, v135 row_mirror row_mask:0xf bank_mask:0xf bound_ctrl:1
	v_add_f32_dpp v52, v52, v52 row_mirror row_mask:0xf bank_mask:0xf bound_ctrl:1
	v_rsq_f32_e32 v115, v115
	v_rsq_f32_e32 v125, v125
	ds_bpermute_b32 v124, v151, v123
	ds_bpermute_b32 v136, v151, v135
	ds_bpermute_b32 v103, v151, v52
	v_mul_f32_e32 v154, v72, v89
	v_mul_f32_e32 v141, v68, v69
	v_mul_f32_e32 v134, v145, v115
	v_mul_f32_e32 v115, v149, v125
	v_mul_f32_e32 v155, v108, v154
	v_mul_f32_e32 v156, v108, v141
	v_mul_f32_e32 v125, v148, v115
	s_waitcnt lgkmcnt(2)
	v_add_f32_e32 v148, v123, v124
	s_waitcnt lgkmcnt(1)
	v_add_f32_e32 v145, v135, v136
	v_mov_b32_dpp v123, v155 quad_perm:[1,0,3,2] row_mask:0xf bank_mask:0xf bound_ctrl:1
	v_mov_b32_dpp v135, v156 quad_perm:[1,0,3,2] row_mask:0xf bank_mask:0xf bound_ctrl:1
	s_waitcnt lgkmcnt(0)
	v_add_f32_e32 v140, v52, v103
	v_mul_f32_e32 v52, v178, v158
	v_fmac_f32_e32 v123, v108, v154
	v_fmac_f32_e32 v135, v108, v141
	v_mov_b32_dpp v52, v52 quad_perm:[1,0,3,2] row_mask:0xf bank_mask:0xf bound_ctrl:1
	v_add_f32_dpp v123, v123, v123 quad_perm:[2,3,0,1] row_mask:0xf bank_mask:0xf bound_ctrl:1
	v_add_f32_dpp v135, v135, v135 quad_perm:[2,3,0,1] row_mask:0xf bank_mask:0xf bound_ctrl:1
	v_fmac_f32_e32 v52, v178, v158
	v_add_f32_dpp v123, v123, v123 row_half_mirror row_mask:0xf bank_mask:0xf bound_ctrl:1
	v_add_f32_dpp v135, v135, v135 row_half_mirror row_mask:0xf bank_mask:0xf bound_ctrl:1
	v_add_f32_dpp v52, v52, v52 quad_perm:[2,3,0,1] row_mask:0xf bank_mask:0xf bound_ctrl:1
	v_add_f32_dpp v123, v123, v123 row_mirror row_mask:0xf bank_mask:0xf bound_ctrl:1
	v_add_f32_dpp v137, v135, v135 row_mirror row_mask:0xf bank_mask:0xf bound_ctrl:1
	v_add_f32_dpp v52, v52, v52 row_half_mirror row_mask:0xf bank_mask:0xf bound_ctrl:1
	ds_bpermute_b32 v124, v151, v123
	ds_bpermute_b32 v139, v151, v137
	v_add_f32_dpp v52, v52, v52 row_mirror row_mask:0xf bank_mask:0xf bound_ctrl:1
	ds_bpermute_b32 v154, v151, v52
	v_mul_f32_e32 v103, v132, v158
	s_waitcnt lgkmcnt(2)
	v_add_f32_e32 v135, v123, v124
	s_waitcnt lgkmcnt(1)
	v_add_f32_e32 v123, v137, v139
	v_mov_b32_dpp v103, v103 quad_perm:[1,0,3,2] row_mask:0xf bank_mask:0xf bound_ctrl:1
	v_fmac_f32_e32 v103, v132, v158
	v_mul_f32_e32 v137, v150, v147
	v_mul_f32_e32 v139, v121, v147
	v_mul_f32_e32 v142, v138, v134
	v_add_f32_dpp v103, v103, v103 quad_perm:[2,3,0,1] row_mask:0xf bank_mask:0xf bound_ctrl:1
	s_waitcnt lgkmcnt(0)
	v_add_f32_e32 v171, v52, v154
	v_mov_b32_dpp v52, v137 quad_perm:[1,0,3,2] row_mask:0xf bank_mask:0xf bound_ctrl:1
	v_add_f32_dpp v103, v103, v103 row_half_mirror row_mask:0xf bank_mask:0xf bound_ctrl:1
	v_mov_b32_dpp v137, v139 quad_perm:[1,0,3,2] row_mask:0xf bank_mask:0xf bound_ctrl:1
	v_mov_b32_dpp v142, v142 quad_perm:[1,0,3,2] row_mask:0xf bank_mask:0xf bound_ctrl:1
	v_add_f32_dpp v103, v103, v103 row_mirror row_mask:0xf bank_mask:0xf bound_ctrl:1
	v_fmac_f32_e32 v137, v121, v147
	v_fmac_f32_e32 v142, v138, v134
	ds_bpermute_b32 v155, v151, v103
	v_add_f32_dpp v137, v137, v137 quad_perm:[2,3,0,1] row_mask:0xf bank_mask:0xf bound_ctrl:1
	v_add_f32_dpp v142, v142, v142 quad_perm:[2,3,0,1] row_mask:0xf bank_mask:0xf bound_ctrl:1
	v_fmac_f32_e32 v52, v150, v147
	v_add_f32_dpp v137, v137, v137 row_half_mirror row_mask:0xf bank_mask:0xf bound_ctrl:1
	v_add_f32_dpp v142, v142, v142 row_half_mirror row_mask:0xf bank_mask:0xf bound_ctrl:1
	v_add_f32_dpp v52, v52, v52 quad_perm:[2,3,0,1] row_mask:0xf bank_mask:0xf bound_ctrl:1
	v_add_f32_dpp v137, v137, v137 row_mirror row_mask:0xf bank_mask:0xf bound_ctrl:1
	v_add_f32_dpp v142, v142, v142 row_mirror row_mask:0xf bank_mask:0xf bound_ctrl:1
	v_add_f32_dpp v52, v52, v52 row_half_mirror row_mask:0xf bank_mask:0xf bound_ctrl:1
	ds_bpermute_b32 v139, v151, v137
	ds_bpermute_b32 v154, v151, v142
	v_add_f32_dpp v52, v52, v52 row_mirror row_mask:0xf bank_mask:0xf bound_ctrl:1
	s_waitcnt lgkmcnt(2)
	v_add_f32_e32 v169, v103, v155
	ds_bpermute_b32 v103, v151, v52
	v_mul_f32_e32 v174, v125, v118
	v_mul_f32_e32 v175, v89, v118
	s_waitcnt lgkmcnt(2)
	v_add_f32_e32 v163, v137, v139
	s_waitcnt lgkmcnt(1)
	v_add_f32_e32 v155, v142, v154
	v_mov_b32_dpp v137, v174 quad_perm:[1,0,3,2] row_mask:0xf bank_mask:0xf bound_ctrl:1
	v_mov_b32_dpp v142, v175 quad_perm:[1,0,3,2] row_mask:0xf bank_mask:0xf bound_ctrl:1
	v_mul_f32_e32 v143, v113, v134
	v_fmac_f32_e32 v137, v125, v118
	v_fmac_f32_e32 v142, v89, v118
	s_waitcnt lgkmcnt(0)
	v_add_f32_e32 v165, v52, v103
	v_mov_b32_dpp v52, v143 quad_perm:[1,0,3,2] row_mask:0xf bank_mask:0xf bound_ctrl:1
	v_add_f32_dpp v137, v137, v137 quad_perm:[2,3,0,1] row_mask:0xf bank_mask:0xf bound_ctrl:1
	v_add_f32_dpp v142, v142, v142 quad_perm:[2,3,0,1] row_mask:0xf bank_mask:0xf bound_ctrl:1
	v_fmac_f32_e32 v52, v113, v134
	v_add_f32_dpp v137, v137, v137 row_half_mirror row_mask:0xf bank_mask:0xf bound_ctrl:1
	v_add_f32_dpp v142, v142, v142 row_half_mirror row_mask:0xf bank_mask:0xf bound_ctrl:1
	v_add_f32_dpp v52, v52, v52 quad_perm:[2,3,0,1] row_mask:0xf bank_mask:0xf bound_ctrl:1
	v_add_f32_dpp v137, v137, v137 row_mirror row_mask:0xf bank_mask:0xf bound_ctrl:1
	v_add_f32_dpp v174, v142, v142 row_mirror row_mask:0xf bank_mask:0xf bound_ctrl:1
	v_add_f32_dpp v52, v52, v52 row_half_mirror row_mask:0xf bank_mask:0xf bound_ctrl:1
	ds_bpermute_b32 v139, v151, v137
	ds_bpermute_b32 v175, v151, v174
	v_add_f32_dpp v52, v52, v52 row_mirror row_mask:0xf bank_mask:0xf bound_ctrl:1
	ds_bpermute_b32 v103, v151, v52
	ds_bpermute_b32 v168, v173, v167
	s_waitcnt lgkmcnt(3)
	v_add_f32_e32 v142, v137, v139
	s_waitcnt lgkmcnt(2)
	v_add_f32_e32 v137, v174, v175
	v_lshlrev_b64 v[174:175], 8, v[96:97]
	v_or_b32_sdwa v174, v174, v111 dst_sel:DWORD dst_unused:UNUSED_PAD src0_sel:DWORD src1_sel:BYTE_0
	s_waitcnt lgkmcnt(1)
	v_add_f32_e32 v151, v52, v103
	v_lshl_add_u64 v[176:177], v[174:175], 2, s[14:15]
	v_lshlrev_b64 v[174:175], 1, v[174:175]
	ds_bpermute_b32 v162, v173, v161
	ds_bpermute_b32 v160, v173, v159
	ds_bpermute_b32 v149, v173, v148
	ds_bpermute_b32 v146, v173, v145
	ds_bpermute_b32 v141, v173, v140
	ds_bpermute_b32 v136, v173, v135
	ds_bpermute_b32 v124, v173, v123
	ds_bpermute_b32 v172, v173, v171
	ds_bpermute_b32 v170, v173, v169
	ds_bpermute_b32 v166, v173, v165
	ds_bpermute_b32 v164, v173, v163
	ds_bpermute_b32 v156, v173, v155
	ds_bpermute_b32 v154, v173, v151
	ds_bpermute_b32 v143, v173, v142
	ds_bpermute_b32 v139, v173, v137
	global_store_dword v[176:177], v120, off
	v_cvt_pk_bf16_f32 v100, v100, v53

	global_store_short v174, v100, s[26:27]
	v_cvt_pk_bf16_f32 v100, v132, v53

	v_bfe_u32 v52, v111, 6, 2
	global_store_short v174, v100, s[28:29]
	v_cvt_pk_bf16_f32 v100, v178, v53

	v_lshlrev_b32_e32 v52, 2, v52
	global_store_short v174, v100, s[30:31]
	v_xor_b32_e32 v100, 0x80000000, v157

	v_cmp_eq_u32_e32 vcc, 0, v102
	v_lshl_add_u64 v[102:103], s[22:23], 0, v[52:53]
	v_cvt_pk_bf16_f32 v100, v100, v53
	global_store_short v174, v100, s[34:35]
	v_lshl_add_u64 v[176:177], s[16:17], 0, v[174:175]

	v_cvt_pk_bf16_f32 v90, v90, v53
	global_store_short v[176:177], v90, off
	v_cvt_pk_bf16_f32 v84, v84, v53
	global_store_short v174, v84, s[18:19]
	s_and_saveexec_b64 s[4:5], vcc

	v_lshl_add_u64 v[96:97], v[96:97], 4, v[102:103]
	s_waitcnt lgkmcnt(14)
	v_add_f32_e32 v84, v167, v168
	global_store_dword v[96:97], v84, off
.LBB0_303:
	s_or_b64 exec, exec, s[4:5]
	v_add_f32_e32 v84, v104, v91
	v_mul_f32_e32 v84, 0xbfb8aa3b, v84
	v_exp_f32_e32 v84, v84
	v_lshl_add_u64 v[90:91], s[24:25], 0, v[52:53]
	v_lshlrev_b64 v[96:97], 8, v[94:95]
	v_or_b32_sdwa v96, v96, v111 dst_sel:DWORD dst_unused:UNUSED_PAD src0_sel:DWORD src1_sel:BYTE_0
	v_add_f32_e32 v84, 1.0, v84
	v_rcp_f32_e32 v84, v84
	s_waitcnt lgkmcnt(7)
	v_add_f32_e32 v132, v171, v172
	v_lshl_add_u64 v[172:173], v[96:97], 2, s[14:15]
	v_lshlrev_b64 v[96:97], 1, v[96:97]
	v_mul_f32_e32 v52, 0xbf1b4598, v84
	v_mul_f32_e32 v52, 0x3fb8aa3b, v52
	v_exp_f32_e32 v52, v52

	v_mul_f32_e32 v100, v127, v158
	global_store_dword v[172:173], v52, off
	v_cvt_pk_bf16_f32 v52, v98, v53
	global_store_short v96, v52, s[26:27]
	v_cvt_pk_bf16_f32 v52, v126, v53

	global_store_short v96, v52, s[28:29]
	v_cvt_pk_bf16_f32 v52, v100, v53

	global_store_short v96, v52, s[30:31]
	v_mul_f32_e32 v52, v120, v158
	v_fma_f32 v52, v157, v132, -v52

	v_cvt_pk_bf16_f32 v52, v52, v53
	global_store_short v96, v52, s[34:35]
	s_and_saveexec_b64 s[4:5], vcc

	s_waitcnt lgkmcnt(6)
	v_add_f32_e32 v52, v169, v170
	v_xor_b32_e32 v52, 0x80000000, v52
	v_lshl_add_u64 v[126:127], v[94:95], 4, v[90:91]
	global_store_dword v[126:127], v52, off
.LBB0_305:
	s_or_b64 exec, exec, s[4:5]
	v_cvt_pk_bf16_f32 v52, v122, v53

	global_store_short v96, v52, s[16:17]
	v_cvt_pk_bf16_f32 v52, v85, v53

	global_store_short v96, v52, s[18:19]
	s_and_saveexec_b64 s[4:5], vcc

	v_add_f32_e32 v52, v161, v162
	v_lshl_add_u64 v[84:85], v[94:95], 4, v[102:103]
	global_store_dword v[84:85], v52, off
.LBB0_307:
	s_or_b64 exec, exec, s[4:5]
	v_add_f32_e32 v52, v104, v74
	v_mul_f32_e32 v52, 0xbfb8aa3b, v52
	v_exp_f32_e32 v52, v52
	v_lshlrev_b64 v[84:85], 8, v[86:87]
	v_or_b32_sdwa v84, v84, v111 dst_sel:DWORD dst_unused:UNUSED_PAD src0_sel:DWORD src1_sel:BYTE_0
	v_lshl_add_u64 v[94:95], v[84:85], 2, s[14:15]
	v_add_f32_e32 v52, 1.0, v52
	v_rcp_f32_e32 v52, v52
	v_lshlrev_b64 v[84:85], 1, v[84:85]


	v_mul_f32_e32 v52, 0xbf1b4598, v52
	v_mul_f32_e32 v52, 0x3fb8aa3b, v52
	v_exp_f32_e32 v52, v52
	global_store_dword v[94:95], v52, off
	v_cvt_pk_bf16_f32 v74, v92, v53
	global_store_short v84, v74, s[26:27]
	v_cvt_pk_bf16_f32 v74, v121, v53
	global_store_short v84, v74, s[28:29]
	v_cvt_pk_bf16_f32 v74, v150, v53

	global_store_short v84, v74, s[30:31]
	v_xor_b32_e32 v74, 0x80000000, v144

	v_cvt_pk_bf16_f32 v74, v74, v53
	global_store_short v84, v74, s[34:35]
	v_lshl_add_u64 v[94:95], s[16:17], 0, v[84:85]

	v_cvt_pk_bf16_f32 v74, v117, v53
	global_store_short v[94:95], v74, off
	v_cvt_pk_bf16_f32 v64, v64, v53
	global_store_short v84, v64, s[18:19]
	s_and_saveexec_b64 s[4:5], vcc

	v_add_f32_e32 v64, v159, v160
	v_lshl_add_u64 v[84:85], v[86:87], 4, v[102:103]
	global_store_dword v[84:85], v64, off
.LBB0_309:
	s_or_b64 exec, exec, s[4:5]
	v_add_f32_e32 v64, v104, v75
	v_mul_f32_e32 v64, 0xbfb8aa3b, v64
	v_exp_f32_e32 v64, v64
	v_lshlrev_b64 v[74:75], 8, v[80:81]
	v_or_b32_sdwa v74, v74, v111 dst_sel:DWORD dst_unused:UNUSED_PAD src0_sel:DWORD src1_sel:BYTE_0
	v_lshl_add_u64 v[84:85], v[74:75], 2, s[14:15]
	v_add_f32_e32 v64, 1.0, v64
	v_rcp_f32_e32 v64, v64
	v_lshlrev_b64 v[74:75], 1, v[74:75]

	s_waitcnt lgkmcnt(5)
	v_add_f32_e32 v94, v165, v166
	v_mul_f32_e32 v64, 0xbf1b4598, v64
	v_mul_f32_e32 v64, 0x3fb8aa3b, v64
	v_exp_f32_e32 v64, v64
	v_mul_f32_e32 v52, v52, v147
	v_mul_f32_e32 v92, v119, v147
	v_fma_f32 v52, v144, v94, -v52
	global_store_dword v[84:85], v64, off
	v_cvt_pk_bf16_f32 v64, v88, v53

	global_store_short v74, v64, s[26:27]
	v_cvt_pk_bf16_f32 v64, v116, v53
	global_store_short v74, v64, s[28:29]

	v_cvt_pk_bf16_f32 v64, v92, v53
	global_store_short v74, v64, s[30:31]

	v_cvt_pk_bf16_f32 v52, v52, v53
	global_store_short v74, v52, s[34:35]
	s_and_saveexec_b64 s[4:5], vcc

	s_waitcnt lgkmcnt(4)
	v_add_f32_e32 v52, v163, v164
	v_xor_b32_e32 v52, 0x80000000, v52
	v_lshl_add_u64 v[84:85], v[80:81], 4, v[90:91]
	global_store_dword v[84:85], v52, off
.LBB0_311:
	s_or_b64 exec, exec, s[4:5]
	v_cvt_pk_bf16_f32 v52, v114, v53

	global_store_short v74, v52, s[16:17]
	v_cvt_pk_bf16_f32 v52, v65, v53

	global_store_short v74, v52, s[18:19]
	s_and_saveexec_b64 s[4:5], vcc

	v_add_f32_e32 v52, v148, v149
	v_lshl_add_u64 v[64:65], v[80:81], 4, v[102:103]
	global_store_dword v[64:65], v52, off
.LBB0_313:
	s_or_b64 exec, exec, s[4:5]
	v_add_f32_e32 v52, v104, v60
	v_mul_f32_e32 v52, 0xbfb8aa3b, v52
	v_exp_f32_e32 v52, v52
	v_lshlrev_b64 v[64:65], 8, v[76:77]
	v_or_b32_sdwa v64, v64, v111 dst_sel:DWORD dst_unused:UNUSED_PAD src0_sel:DWORD src1_sel:BYTE_0
	v_lshl_add_u64 v[74:75], v[64:65], 2, s[14:15]
	v_add_f32_e32 v52, 1.0, v52
	v_rcp_f32_e32 v52, v52
	v_lshlrev_b64 v[64:65], 1, v[64:65]


	v_mul_f32_e32 v52, 0xbf1b4598, v52
	v_mul_f32_e32 v52, 0x3fb8aa3b, v52
	v_exp_f32_e32 v52, v52
	global_store_dword v[74:75], v52, off
	v_cvt_pk_bf16_f32 v60, v82, v53
	global_store_short v64, v60, s[26:27]
	v_cvt_pk_bf16_f32 v60, v113, v53
	global_store_short v64, v60, s[28:29]
	v_cvt_pk_bf16_f32 v60, v138, v53

	global_store_short v64, v60, s[30:31]
	v_xor_b32_e32 v60, 0x80000000, v133

	v_cvt_pk_bf16_f32 v60, v60, v53
	global_store_short v64, v60, s[34:35]
	v_lshl_add_u64 v[74:75], s[16:17], 0, v[64:65]

	v_cvt_pk_bf16_f32 v60, v101, v53
	global_store_short v[74:75], v60, off
	v_cvt_pk_bf16_f32 v58, v58, v53
	global_store_short v64, v58, s[18:19]
	s_and_saveexec_b64 s[4:5], vcc

	v_add_f32_e32 v58, v145, v146
	v_lshl_add_u64 v[64:65], v[76:77], 4, v[102:103]
	global_store_dword v[64:65], v58, off
.LBB0_315:
	s_or_b64 exec, exec, s[4:5]
	v_add_f32_e32 v58, v104, v61
	v_mul_f32_e32 v58, 0xbfb8aa3b, v58
	v_exp_f32_e32 v58, v58
	v_lshlrev_b64 v[60:61], 8, v[70:71]
	v_or_b32_sdwa v60, v60, v111 dst_sel:DWORD dst_unused:UNUSED_PAD src0_sel:DWORD src1_sel:BYTE_0
	v_lshl_add_u64 v[64:65], v[60:61], 2, s[14:15]
	v_add_f32_e32 v58, 1.0, v58
	v_rcp_f32_e32 v58, v58
	v_lshlrev_b64 v[60:61], 1, v[60:61]

	s_waitcnt lgkmcnt(3)
	v_add_f32_e32 v77, v155, v156
	v_mul_f32_e32 v58, 0xbf1b4598, v58
	v_mul_f32_e32 v58, 0x3fb8aa3b, v58
	v_exp_f32_e32 v58, v58
	v_mul_f32_e32 v52, v52, v134
	v_mul_f32_e32 v76, v112, v134
	v_fma_f32 v52, v133, v77, -v52
	global_store_dword v[64:65], v58, off
	v_cvt_pk_bf16_f32 v58, v78, v53

	global_store_short v60, v58, s[26:27]
	v_cvt_pk_bf16_f32 v58, v99, v53
	global_store_short v60, v58, s[28:29]

	v_cvt_pk_bf16_f32 v58, v76, v53
	global_store_short v60, v58, s[30:31]

	v_cvt_pk_bf16_f32 v52, v52, v53
	global_store_short v60, v52, s[34:35]
	s_and_saveexec_b64 s[4:5], vcc

	s_waitcnt lgkmcnt(2)
	v_add_f32_e32 v52, v151, v154
	v_xor_b32_e32 v52, 0x80000000, v52
	v_lshl_add_u64 v[64:65], v[70:71], 4, v[90:91]
	global_store_dword v[64:65], v52, off
.LBB0_317:
	s_or_b64 exec, exec, s[4:5]
	v_cvt_pk_bf16_f32 v52, v93, v53

	global_store_short v60, v52, s[16:17]
	v_cvt_pk_bf16_f32 v52, v59, v53

	global_store_short v60, v52, s[18:19]
	s_and_saveexec_b64 s[4:5], vcc

	v_add_f32_e32 v52, v140, v141
	v_lshl_add_u64 v[58:59], v[70:71], 4, v[102:103]
	global_store_dword v[58:59], v52, off
.LBB0_319:
	s_or_b64 exec, exec, s[4:5]
	v_add_f32_e32 v52, v104, v56
	v_mul_f32_e32 v52, 0xbfb8aa3b, v52
	v_exp_f32_e32 v52, v52
	v_lshlrev_b64 v[58:59], 8, v[66:67]
	v_or_b32_sdwa v58, v58, v111 dst_sel:DWORD dst_unused:UNUSED_PAD src0_sel:DWORD src1_sel:BYTE_0
	v_lshl_add_u64 v[60:61], v[58:59], 2, s[14:15]
	v_add_f32_e32 v52, 1.0, v52
	v_rcp_f32_e32 v52, v52
	v_lshlrev_b64 v[58:59], 1, v[58:59]


	v_mul_f32_e32 v52, 0xbf1b4598, v52
	v_mul_f32_e32 v52, 0x3fb8aa3b, v52
	v_exp_f32_e32 v52, v52
	global_store_dword v[60:61], v52, off
	v_cvt_pk_bf16_f32 v56, v72, v53
	global_store_short v58, v56, s[26:27]
	v_cvt_pk_bf16_f32 v56, v89, v53
	global_store_short v58, v56, s[28:29]
	v_cvt_pk_bf16_f32 v56, v125, v53

	global_store_short v58, v56, s[30:31]
	v_xor_b32_e32 v56, 0x80000000, v115

	v_cvt_pk_bf16_f32 v56, v56, v53
	global_store_short v58, v56, s[34:35]
	v_lshl_add_u64 v[60:61], s[16:17], 0, v[58:59]

	v_cvt_pk_bf16_f32 v56, v79, v53
	global_store_short v[60:61], v56, off
	v_cvt_pk_bf16_f32 v54, v54, v53
	global_store_short v58, v54, s[18:19]
	s_and_saveexec_b64 s[4:5], vcc

	v_add_f32_e32 v54, v135, v136
	v_lshl_add_u64 v[58:59], v[66:67], 4, v[102:103]
	global_store_dword v[58:59], v54, off
.LBB0_321:
	s_or_b64 exec, exec, s[4:5]
	v_add_f32_e32 v54, v104, v57
	v_mul_f32_e32 v54, 0xbfb8aa3b, v54
	v_exp_f32_e32 v54, v54
	v_lshlrev_b64 v[56:57], 8, v[62:63]
	v_or_b32_sdwa v56, v56, v111 dst_sel:DWORD dst_unused:UNUSED_PAD src0_sel:DWORD src1_sel:BYTE_0
	v_lshl_add_u64 v[58:59], v[56:57], 2, s[14:15]
	v_add_f32_e32 v54, 1.0, v54
	v_rcp_f32_e32 v54, v54
	v_lshlrev_b64 v[56:57], 1, v[56:57]

	s_waitcnt lgkmcnt(1)
	v_add_f32_e32 v65, v142, v143
	v_mul_f32_e32 v54, 0xbf1b4598, v54
	v_mul_f32_e32 v54, 0x3fb8aa3b, v54
	v_exp_f32_e32 v54, v54
	v_mul_f32_e32 v52, v52, v118
	v_mul_f32_e32 v64, v83, v118
	v_fma_f32 v52, v115, v65, -v52
	global_store_dword v[58:59], v54, off
	v_cvt_pk_bf16_f32 v54, v68, v53

	global_store_short v56, v54, s[26:27]
	v_cvt_pk_bf16_f32 v54, v69, v53
	global_store_short v56, v54, s[28:29]

	v_cvt_pk_bf16_f32 v54, v64, v53
	global_store_short v56, v54, s[30:31]

	v_cvt_pk_bf16_f32 v52, v52, v53
	global_store_short v56, v52, s[34:35]
	s_and_saveexec_b64 s[4:5], vcc

	s_waitcnt lgkmcnt(0)
	v_add_f32_e32 v52, v137, v139
	v_xor_b32_e32 v52, 0x80000000, v52
	v_lshl_add_u64 v[58:59], v[62:63], 4, v[90:91]
	global_store_dword v[58:59], v52, off

.LBB0_1049:
	s_add_i32 s55, s55, s54
	s_cmpk_lt_i32 s55, 0x400
	s_cselect_b64 s[46:47], -1, 0
	s_cmpk_gt_i32 s55, 0x3ff
	v_mov_b32_e32 v139, v152
	s_cselect_b64 s[42:43], -1, 0
	s_nop 0
	v_cmp_gt_i32_e32 vcc, s57, v139
	v_lshlrev_b32_e32 v70, 1, v139
	s_barrier
	s_and_saveexec_b64 s[44:45], vcc
	s_cbranch_execz .LBB0_1183
	s_waitcnt vmcnt(22)
	v_and_b32_e32 v73, 0xffff0000, v1
	v_lshlrev_b32_e32 v72, 16, v1
	v_and_b32_e32 v75, 0xffff0000, v0
	v_lshlrev_b32_e32 v74, 16, v0
	v_pk_add_f32 v[74:75], v[74:75], v[72:73] neg_lo:[0,1] neg_hi:[0,1]
	v_cmp_lt_i32_e64 s[6:7], s58, v139
	v_cmp_lt_u32_e64 s[4:5], s59, v139
	v_cmp_lt_u32_e32 vcc, s60, v139
	s_waitcnt vmcnt(6)
	v_pk_fma_f32 v[74:75], v[66:67], v[74:75], v[72:73]
	s_and_saveexec_b64 s[48:49], s[6:7]
	s_cbranch_execz .LBB0_1058
	s_and_saveexec_b64 s[40:41], s[4:5]
	s_xor_b64 s[50:51], exec, s[40:41]
	s_cbranch_execz .LBB0_1055
	s_and_saveexec_b64 s[52:53], vcc

	v_mul_f32_e32 v68, 0xbfb8aa3b, v74
	v_mul_f32_e32 v71, 0xbfb8aa3b, v75
	v_exp_f32_e32 v68, v68
	v_exp_f32_e32 v71, v71
	v_add_f32_e32 v68, 1.0, v68
	v_add_f32_e32 v71, 1.0, v71
	v_rcp_f32_e32 v74, v68
	v_rcp_f32_e32 v75, v71

.LBB0_1058:
	s_or_b64 exec, exec, s[48:49]
	v_lshl_add_u32 v68, v70, 2, 0
	ds_write_b64 v68, v[74:75]
	v_and_b32_e32 v75, 0xffff0000, v2
	v_lshlrev_b32_e32 v74, 16, v2
	v_pk_add_f32 v[72:73], v[72:73], v[74:75] neg_lo:[0,1] neg_hi:[0,1]
	s_nop 0
	v_pk_fma_f32 v[72:73], v[66:67], v[72:73], v[74:75]
	s_and_saveexec_b64 s[48:49], s[6:7]
	s_cbranch_execz .LBB0_1066
	s_and_saveexec_b64 s[40:41], s[4:5]
	s_xor_b64 s[50:51], exec, s[40:41]
	s_cbranch_execz .LBB0_1063
	s_and_saveexec_b64 s[52:53], vcc

	v_mul_f32_e32 v71, 0xbfb8aa3b, v72
	v_mul_f32_e32 v72, 0xbfb8aa3b, v73
	v_exp_f32_e32 v71, v71
	v_exp_f32_e32 v72, v72
	v_add_f32_e32 v71, 1.0, v71
	v_add_f32_e32 v73, 1.0, v72
	v_rcp_f32_e32 v72, v71
	v_rcp_f32_e32 v73, v73

.LBB0_1066:
	s_or_b64 exec, exec, s[48:49]
	ds_write_b64 v68, v[72:73] offset:3600
	v_and_b32_e32 v73, 0xffff0000, v3
	v_lshlrev_b32_e32 v72, 16, v3
	v_pk_add_f32 v[74:75], v[74:75], v[72:73] neg_lo:[0,1] neg_hi:[0,1]
	s_nop 0
	v_pk_fma_f32 v[74:75], v[66:67], v[74:75], v[72:73]
	s_and_saveexec_b64 s[48:49], s[6:7]
	s_cbranch_execz .LBB0_1074
	s_and_saveexec_b64 s[40:41], s[4:5]
	s_xor_b64 s[50:51], exec, s[40:41]
	s_cbranch_execz .LBB0_1071
	s_and_saveexec_b64 s[52:53], vcc

	v_mul_f32_e32 v71, 0xbfb8aa3b, v74
	v_mul_f32_e32 v74, 0xbfb8aa3b, v75
	v_exp_f32_e32 v71, v71
	v_exp_f32_e32 v74, v74
	v_add_f32_e32 v71, 1.0, v71
	v_add_f32_e32 v75, 1.0, v74
	v_rcp_f32_e32 v74, v71
	v_rcp_f32_e32 v75, v75

.LBB0_1074:
	s_or_b64 exec, exec, s[48:49]
	ds_write_b64 v68, v[74:75] offset:7200
	v_and_b32_e32 v75, 0xffff0000, v4
	v_lshlrev_b32_e32 v74, 16, v4
	v_pk_add_f32 v[72:73], v[72:73], v[74:75] neg_lo:[0,1] neg_hi:[0,1]
	s_nop 0
	v_pk_fma_f32 v[72:73], v[66:67], v[72:73], v[74:75]
	s_and_saveexec_b64 s[48:49], s[6:7]
	s_cbranch_execz .LBB0_1082
	s_and_saveexec_b64 s[40:41], s[4:5]
	s_xor_b64 s[50:51], exec, s[40:41]
	s_cbranch_execz .LBB0_1079
	s_and_saveexec_b64 s[52:53], vcc

	v_mul_f32_e32 v71, 0xbfb8aa3b, v72
	v_mul_f32_e32 v72, 0xbfb8aa3b, v73
	v_exp_f32_e32 v71, v71
	v_exp_f32_e32 v72, v72
	v_add_f32_e32 v71, 1.0, v71
	v_add_f32_e32 v73, 1.0, v72
	v_rcp_f32_e32 v72, v71
	v_rcp_f32_e32 v73, v73

.LBB0_1082:
	s_or_b64 exec, exec, s[48:49]
	ds_write_b64 v68, v[72:73] offset:10800
	v_and_b32_e32 v73, 0xffff0000, v5
	v_lshlrev_b32_e32 v72, 16, v5
	v_pk_add_f32 v[74:75], v[74:75], v[72:73] neg_lo:[0,1] neg_hi:[0,1]
	s_nop 0
	v_pk_fma_f32 v[74:75], v[66:67], v[74:75], v[72:73]
	s_and_saveexec_b64 s[48:49], s[6:7]
	s_cbranch_execz .LBB0_1090
	s_and_saveexec_b64 s[40:41], s[4:5]
	s_xor_b64 s[50:51], exec, s[40:41]
	s_cbranch_execz .LBB0_1087
	s_and_saveexec_b64 s[52:53], vcc

	v_mul_f32_e32 v71, 0xbfb8aa3b, v74
	v_mul_f32_e32 v74, 0xbfb8aa3b, v75
	v_exp_f32_e32 v71, v71
	v_exp_f32_e32 v74, v74
	v_add_f32_e32 v71, 1.0, v71
	v_add_f32_e32 v75, 1.0, v74
	v_rcp_f32_e32 v74, v71
	v_rcp_f32_e32 v75, v75

.LBB0_1090:
	s_or_b64 exec, exec, s[48:49]
	ds_write_b64 v68, v[74:75] offset:14400
	v_and_b32_e32 v75, 0xffff0000, v6
	v_lshlrev_b32_e32 v74, 16, v6
	v_pk_add_f32 v[72:73], v[72:73], v[74:75] neg_lo:[0,1] neg_hi:[0,1]
	s_nop 0
	v_pk_fma_f32 v[72:73], v[66:67], v[72:73], v[74:75]
	s_and_saveexec_b64 s[48:49], s[6:7]
	s_cbranch_execz .LBB0_1098
	s_and_saveexec_b64 s[40:41], s[4:5]
	s_xor_b64 s[50:51], exec, s[40:41]
	s_cbranch_execz .LBB0_1095
	s_and_saveexec_b64 s[52:53], vcc

	v_mul_f32_e32 v71, 0xbfb8aa3b, v72
	v_mul_f32_e32 v72, 0xbfb8aa3b, v73
	v_exp_f32_e32 v71, v71
	v_exp_f32_e32 v72, v72
	v_add_f32_e32 v71, 1.0, v71
	v_add_f32_e32 v73, 1.0, v72
	v_rcp_f32_e32 v72, v71
	v_rcp_f32_e32 v73, v73

.LBB0_1098:
	s_or_b64 exec, exec, s[48:49]
	ds_write_b64 v68, v[72:73] offset:18000
	v_and_b32_e32 v73, 0xffff0000, v7
	v_lshlrev_b32_e32 v72, 16, v7
	v_pk_add_f32 v[74:75], v[74:75], v[72:73] neg_lo:[0,1] neg_hi:[0,1]
	s_nop 0
	v_pk_fma_f32 v[74:75], v[66:67], v[74:75], v[72:73]
	s_and_saveexec_b64 s[48:49], s[6:7]
	s_cbranch_execz .LBB0_1106
	s_and_saveexec_b64 s[40:41], s[4:5]
	s_xor_b64 s[50:51], exec, s[40:41]
	s_cbranch_execz .LBB0_1103
	s_and_saveexec_b64 s[52:53], vcc

	v_mul_f32_e32 v71, 0xbfb8aa3b, v74
	v_mul_f32_e32 v74, 0xbfb8aa3b, v75
	v_exp_f32_e32 v71, v71
	v_exp_f32_e32 v74, v74
	v_add_f32_e32 v71, 1.0, v71
	v_add_f32_e32 v75, 1.0, v74
	v_rcp_f32_e32 v74, v71
	v_rcp_f32_e32 v75, v75

.LBB0_1106:
	s_or_b64 exec, exec, s[48:49]
	ds_write_b64 v68, v[74:75] offset:21600
	v_and_b32_e32 v75, 0xffff0000, v8
	v_lshlrev_b32_e32 v74, 16, v8
	v_pk_add_f32 v[72:73], v[72:73], v[74:75] neg_lo:[0,1] neg_hi:[0,1]
	s_nop 0
	v_pk_fma_f32 v[72:73], v[66:67], v[72:73], v[74:75]
	s_and_saveexec_b64 s[48:49], s[6:7]
	s_cbranch_execz .LBB0_1114
	s_and_saveexec_b64 s[40:41], s[4:5]
	s_xor_b64 s[50:51], exec, s[40:41]
	s_cbranch_execz .LBB0_1111
	s_and_saveexec_b64 s[52:53], vcc

	v_mul_f32_e32 v71, 0xbfb8aa3b, v72
	v_mul_f32_e32 v72, 0xbfb8aa3b, v73
	v_exp_f32_e32 v71, v71
	v_exp_f32_e32 v72, v72
	v_add_f32_e32 v71, 1.0, v71
	v_add_f32_e32 v73, 1.0, v72
	v_rcp_f32_e32 v72, v71
	v_rcp_f32_e32 v73, v73

.LBB0_1114:
	s_or_b64 exec, exec, s[48:49]
	ds_write_b64 v68, v[72:73] offset:25200
	v_and_b32_e32 v73, 0xffff0000, v9
	v_lshlrev_b32_e32 v72, 16, v9
	v_pk_add_f32 v[74:75], v[74:75], v[72:73] neg_lo:[0,1] neg_hi:[0,1]
	s_nop 0
	v_pk_fma_f32 v[74:75], v[66:67], v[74:75], v[72:73]
	s_and_saveexec_b64 s[48:49], s[6:7]
	s_cbranch_execz .LBB0_1122
	s_and_saveexec_b64 s[40:41], s[4:5]
	s_xor_b64 s[50:51], exec, s[40:41]
	s_cbranch_execz .LBB0_1119
	s_and_saveexec_b64 s[52:53], vcc

	v_mul_f32_e32 v71, 0xbfb8aa3b, v74
	v_mul_f32_e32 v74, 0xbfb8aa3b, v75
	v_exp_f32_e32 v71, v71
	v_exp_f32_e32 v74, v74
	v_add_f32_e32 v71, 1.0, v71
	v_add_f32_e32 v75, 1.0, v74
	v_rcp_f32_e32 v74, v71
	v_rcp_f32_e32 v75, v75

.LBB0_1122:
	s_or_b64 exec, exec, s[48:49]
	ds_write_b64 v68, v[74:75] offset:28800
	v_and_b32_e32 v75, 0xffff0000, v10
	v_lshlrev_b32_e32 v74, 16, v10
	v_pk_add_f32 v[72:73], v[72:73], v[74:75] neg_lo:[0,1] neg_hi:[0,1]
	s_nop 0
	v_pk_fma_f32 v[72:73], v[66:67], v[72:73], v[74:75]
	s_and_saveexec_b64 s[48:49], s[6:7]
	s_cbranch_execz .LBB0_1130
	s_and_saveexec_b64 s[40:41], s[4:5]
	s_xor_b64 s[50:51], exec, s[40:41]
	s_cbranch_execz .LBB0_1127
	s_and_saveexec_b64 s[52:53], vcc

	v_mul_f32_e32 v71, 0xbfb8aa3b, v72
	v_mul_f32_e32 v72, 0xbfb8aa3b, v73
	v_exp_f32_e32 v71, v71
	v_exp_f32_e32 v72, v72
	v_add_f32_e32 v71, 1.0, v71
	v_add_f32_e32 v73, 1.0, v72
	v_rcp_f32_e32 v72, v71
	v_rcp_f32_e32 v73, v73

.LBB0_1130:
	s_or_b64 exec, exec, s[48:49]
	ds_write_b64 v68, v[72:73] offset:32400
	v_and_b32_e32 v73, 0xffff0000, v11
	v_lshlrev_b32_e32 v72, 16, v11
	v_pk_add_f32 v[74:75], v[74:75], v[72:73] neg_lo:[0,1] neg_hi:[0,1]
	s_nop 0
	v_pk_fma_f32 v[74:75], v[66:67], v[74:75], v[72:73]
	s_and_saveexec_b64 s[48:49], s[6:7]
	s_cbranch_execz .LBB0_1138
	s_and_saveexec_b64 s[40:41], s[4:5]
	s_xor_b64 s[50:51], exec, s[40:41]
	s_cbranch_execz .LBB0_1135
	s_and_saveexec_b64 s[52:53], vcc

	v_mul_f32_e32 v71, 0xbfb8aa3b, v74
	v_mul_f32_e32 v74, 0xbfb8aa3b, v75
	v_exp_f32_e32 v71, v71
	v_exp_f32_e32 v74, v74
	v_add_f32_e32 v71, 1.0, v71
	v_add_f32_e32 v75, 1.0, v74
	v_rcp_f32_e32 v74, v71
	v_rcp_f32_e32 v75, v75

.LBB0_1138:
	s_or_b64 exec, exec, s[48:49]
	ds_write_b64 v68, v[74:75] offset:36000
	v_and_b32_e32 v75, 0xffff0000, v12
	v_lshlrev_b32_e32 v74, 16, v12
	v_pk_add_f32 v[72:73], v[72:73], v[74:75] neg_lo:[0,1] neg_hi:[0,1]
	s_nop 0
	v_pk_fma_f32 v[72:73], v[66:67], v[72:73], v[74:75]
	s_and_saveexec_b64 s[48:49], s[6:7]
	s_cbranch_execz .LBB0_1146
	s_and_saveexec_b64 s[40:41], s[4:5]
	s_xor_b64 s[50:51], exec, s[40:41]
	s_cbranch_execz .LBB0_1143
	s_and_saveexec_b64 s[52:53], vcc

	v_mul_f32_e32 v71, 0xbfb8aa3b, v72
	v_mul_f32_e32 v72, 0xbfb8aa3b, v73
	v_exp_f32_e32 v71, v71
	v_exp_f32_e32 v72, v72
	v_add_f32_e32 v71, 1.0, v71
	v_add_f32_e32 v73, 1.0, v72
	v_rcp_f32_e32 v72, v71
	v_rcp_f32_e32 v73, v73

.LBB0_1146:
	s_or_b64 exec, exec, s[48:49]
	ds_write_b64 v68, v[72:73] offset:39600
	v_and_b32_e32 v73, 0xffff0000, v13
	v_lshlrev_b32_e32 v72, 16, v13
	v_pk_add_f32 v[74:75], v[74:75], v[72:73] neg_lo:[0,1] neg_hi:[0,1]
	s_nop 0
	v_pk_fma_f32 v[74:75], v[66:67], v[74:75], v[72:73]
	s_and_saveexec_b64 s[48:49], s[6:7]
	s_cbranch_execz .LBB0_1154
	s_and_saveexec_b64 s[40:41], s[4:5]
	s_xor_b64 s[50:51], exec, s[40:41]
	s_cbranch_execz .LBB0_1151
	s_and_saveexec_b64 s[52:53], vcc

	v_mul_f32_e32 v71, 0xbfb8aa3b, v74
	v_mul_f32_e32 v74, 0xbfb8aa3b, v75
	v_exp_f32_e32 v71, v71
	v_exp_f32_e32 v74, v74
	v_add_f32_e32 v71, 1.0, v71
	v_add_f32_e32 v75, 1.0, v74
	v_rcp_f32_e32 v74, v71
	v_rcp_f32_e32 v75, v75

.LBB0_1154:
	s_or_b64 exec, exec, s[48:49]
	ds_write_b64 v68, v[74:75] offset:43200
	v_and_b32_e32 v75, 0xffff0000, v14
	v_lshlrev_b32_e32 v74, 16, v14
	v_pk_add_f32 v[72:73], v[72:73], v[74:75] neg_lo:[0,1] neg_hi:[0,1]
	s_nop 0
	v_pk_fma_f32 v[72:73], v[66:67], v[72:73], v[74:75]
	s_and_saveexec_b64 s[48:49], s[6:7]
	s_cbranch_execz .LBB0_1162
	s_and_saveexec_b64 s[40:41], s[4:5]
	s_xor_b64 s[50:51], exec, s[40:41]
	s_cbranch_execz .LBB0_1159
	s_and_saveexec_b64 s[52:53], vcc

	v_mul_f32_e32 v71, 0xbfb8aa3b, v72
	v_mul_f32_e32 v72, 0xbfb8aa3b, v73
	v_exp_f32_e32 v71, v71
	v_exp_f32_e32 v72, v72
	v_add_f32_e32 v71, 1.0, v71
	v_add_f32_e32 v73, 1.0, v72
	v_rcp_f32_e32 v72, v71
	v_rcp_f32_e32 v73, v73

.LBB0_1162:
	s_or_b64 exec, exec, s[48:49]
	ds_write_b64 v68, v[72:73] offset:46800
	v_and_b32_e32 v73, 0xffff0000, v15
	v_lshlrev_b32_e32 v72, 16, v15
	v_pk_add_f32 v[74:75], v[74:75], v[72:73] neg_lo:[0,1] neg_hi:[0,1]
	s_nop 0
	v_pk_fma_f32 v[74:75], v[66:67], v[74:75], v[72:73]
	s_and_saveexec_b64 s[48:49], s[6:7]
	s_cbranch_execz .LBB0_1170
	s_and_saveexec_b64 s[40:41], s[4:5]
	s_xor_b64 s[50:51], exec, s[40:41]
	s_cbranch_execz .LBB0_1167
	s_and_saveexec_b64 s[52:53], vcc

	v_mul_f32_e32 v71, 0xbfb8aa3b, v74
	v_mul_f32_e32 v74, 0xbfb8aa3b, v75
	v_exp_f32_e32 v71, v71
	v_exp_f32_e32 v74, v74
	v_add_f32_e32 v71, 1.0, v71
	v_add_f32_e32 v75, 1.0, v74
	v_rcp_f32_e32 v74, v71
	v_rcp_f32_e32 v75, v75

.LBB0_1170:
	s_or_b64 exec, exec, s[48:49]
	ds_write_b64 v68, v[74:75] offset:50400
	v_and_b32_e32 v75, 0xffff0000, v16
	v_lshlrev_b32_e32 v74, 16, v16
	v_pk_add_f32 v[72:73], v[72:73], v[74:75] neg_lo:[0,1] neg_hi:[0,1]
	s_nop 0
	v_pk_fma_f32 v[72:73], v[66:67], v[72:73], v[74:75]
	s_and_saveexec_b64 s[48:49], s[6:7]
	s_cbranch_execz .LBB0_1178
	s_and_saveexec_b64 s[6:7], s[4:5]
	s_xor_b64 s[4:5], exec, s[6:7]
	s_cbranch_execz .LBB0_1175
	s_and_saveexec_b64 s[6:7], vcc

	v_mul_f32_e32 v71, 0xbfb8aa3b, v72
	v_mul_f32_e32 v72, 0xbfb8aa3b, v73
	v_exp_f32_e32 v71, v71
	v_exp_f32_e32 v72, v72
	v_add_f32_e32 v71, 1.0, v71
	v_add_f32_e32 v73, 1.0, v72
	v_rcp_f32_e32 v72, v71
	v_rcp_f32_e32 v73, v73

.LBB0_1182:
	v_lshlrev_b32_e32 v72, 1, v70
	s_lshl_b64 s[4:5], s[10:11], 11
	s_add_u32 s4, s8, s4
	s_addc_u32 s5, s9, s5
	global_load_dword v1, v72, s[4:5]
	global_load_dword v2, v72, s[4:5] offset:2048
	s_add_u32 s4, s4, 0x1000
	s_addc_u32 s5, s5, 0
	global_load_dword v3, v72, s[4:5]
	global_load_dword v4, v72, s[4:5] offset:2048
	s_add_u32 s4, s4, 0x1000
	s_addc_u32 s5, s5, 0
	global_load_dword v5, v72, s[4:5]
	global_load_dword v6, v72, s[4:5] offset:2048
	s_add_u32 s4, s4, 0x1000
	s_addc_u32 s5, s5, 0
	global_load_dword v7, v72, s[4:5]
	global_load_dword v8, v72, s[4:5] offset:2048
	s_add_u32 s4, s4, 0x1000
	s_addc_u32 s5, s5, 0
	global_load_dword v9, v72, s[4:5]
	global_load_dword v10, v72, s[4:5] offset:2048
	s_add_u32 s4, s4, 0x1000
	s_addc_u32 s5, s5, 0
	global_load_dword v11, v72, s[4:5]
	global_load_dword v12, v72, s[4:5] offset:2048
	s_add_u32 s4, s4, 0x1000
	s_addc_u32 s5, s5, 0
	global_load_dword v13, v72, s[4:5]
	global_load_dword v14, v72, s[4:5] offset:2048
	s_add_u32 s4, s4, 0x1000
	s_addc_u32 s5, s5, 0
	global_load_dword v15, v72, s[4:5]
	global_load_dword v16, v72, s[4:5] offset:2048
	s_or_b32 s10, s10, 15
.LBB0_1183:
	s_or_b64 exec, exec, s[44:45]
	v_lshl_add_u32 v68, v139, 2, 0
	ds_write_b32 v68, v69 offset:57600
	v_and_b32_e32 v68, 15, v139
	v_bfe_u32 v106, v139, 4, 2
	v_mul_u32_u24_e32 v71, 0xe10, v68
	v_and_b32_e32 v107, 0xffffff80, v70
	v_lshlrev_b32_e32 v70, 5, v106
	v_add3_u32 v94, 0, v71, v70
	v_add_u32_e32 v74, v94, v107
	s_waitcnt lgkmcnt(0)
	s_barrier
	ds_read_b128 v[70:73], v74 offset:2048
	ds_read_b128 v[74:77], v74 offset:2064
	s_waitcnt lgkmcnt(1)
	v_cvt_pk_bf16_f32 v70, v70, v71
	v_cvt_pk_bf16_f32 v71, v72, v73
	s_waitcnt lgkmcnt(0)
	v_cvt_pk_bf16_f32 v72, v74, v75
	v_cvt_pk_bf16_f32 v73, v76, v77
	v_lshl_add_u32 v108, v106, 9, 0
	v_mfma_f32_16x16x32_bf16 v[74:77], v[70:73], v[38:41], 0
	v_lshlrev_b32_e32 v109, 2, v68
	v_add_u32_e32 v78, v108, v109
	s_nop 5
	ds_add_f32 v78, v74 offset:57600
	ds_add_f32 v78, v75 offset:57728
	ds_add_f32 v78, v76 offset:57856
	ds_add_f32 v78, v77 offset:57984
	v_mfma_f32_16x16x32_bf16 v[70:73], v[70:73], v[62:65], 0
	s_nop 7
	ds_add_f32 v78, v70 offset:57664
	ds_add_f32 v78, v71 offset:57792
	ds_add_f32 v78, v72 offset:57920
	ds_add_f32 v78, v73 offset:58048
	s_waitcnt lgkmcnt(0)
	s_barrier
	ds_read_b128 v[70:73], v94 offset:3072
	ds_read_b128 v[74:77], v94 offset:3088
	s_waitcnt lgkmcnt(1)
	v_cvt_pk_bf16_f32 v70, v70, v71
	v_cvt_pk_bf16_f32 v71, v72, v73
	s_waitcnt lgkmcnt(0)
	v_cvt_pk_bf16_f32 v72, v74, v75
	v_cvt_pk_bf16_f32 v73, v76, v77
	ds_read_b128 v[74:77], v94 offset:3200
	ds_read_b128 v[78:81], v94 offset:3216
	s_waitcnt lgkmcnt(1)
	v_cvt_pk_bf16_f32 v74, v74, v75
	v_cvt_pk_bf16_f32 v75, v76, v77
	s_waitcnt lgkmcnt(0)
	v_cvt_pk_bf16_f32 v76, v78, v79
	v_cvt_pk_bf16_f32 v77, v80, v81
	ds_read_b128 v[78:81], v94 offset:3328
	ds_read_b128 v[82:85], v94 offset:3344
	s_waitcnt lgkmcnt(1)
	v_cvt_pk_bf16_f32 v78, v78, v79
	v_cvt_pk_bf16_f32 v79, v80, v81
	s_waitcnt lgkmcnt(0)
	v_cvt_pk_bf16_f32 v80, v82, v83
	v_cvt_pk_bf16_f32 v81, v84, v85
	ds_read_b128 v[82:85], v94 offset:3456
	ds_read_b128 v[86:89], v94 offset:3472
	v_mfma_f32_16x16x32_bf16 v[98:101], v[78:81], v[26:29], 0
	v_mad_i32_i24 v68, v68, s62, v94
	s_waitcnt lgkmcnt(1)
	v_cvt_pk_bf16_f32 v82, v82, v83
	v_mfma_f32_16x16x32_bf16 v[78:81], v[78:81], v[50:53], 0
	v_cvt_pk_bf16_f32 v83, v84, v85
	s_waitcnt lgkmcnt(0)
	v_cvt_pk_bf16_f32 v84, v86, v87
	v_cvt_pk_bf16_f32 v85, v88, v89
	v_mfma_f32_16x16x32_bf16 v[90:93], v[70:73], v[18:21], 0
	ds_read_b128 v[94:97], v68 offset:57600
	ds_read_b128 v[102:105], v68 offset:57616
	v_mad_u32_u24 v68, v106, s63, v108
	v_mfma_f32_16x16x32_bf16 v[70:73], v[70:73], v[42:45], 0
	s_waitcnt lgkmcnt(1)
	v_cvt_pk_bf16_f32 v94, v94, v95
	v_add3_u32 v68, v68, v107, v109
	v_cvt_pk_bf16_f32 v95, v96, v97
	v_mfma_f32_16x16x32_bf16 v[86:89], v[74:77], v[22:25], 0
	s_waitcnt lgkmcnt(0)
	v_cvt_pk_bf16_f32 v96, v102, v103
	v_cvt_pk_bf16_f32 v97, v104, v105
	v_add_u32_e32 v106, 0xe900, v68
	v_mfma_f32_16x16x32_bf16 v[74:77], v[74:77], v[46:49], 0
	s_ashr_i32 s37, s36, 31
	v_mfma_f32_16x16x32_bf16 v[98:101], v[82:85], v[30:33], v[98:101]
	v_mfma_f32_16x16x32_bf16 v[78:81], v[82:85], v[54:57], v[78:81]
	v_mfma_f32_16x16x32_bf16 v[102:105], v[94:97], v[34:37], 0
	v_mfma_f32_16x16x32_bf16 v[82:85], v[94:97], v[58:61], 0
	v_add_u32_e32 v94, 0xe800, v68
	ds_write2_b32 v94, v90, v70 offset0:64 offset1:80
	v_add_u32_e32 v70, 0x4000, v106
	ds_write2_b32 v70, v86, v74 offset1:16
	v_add_u32_e32 v70, 0x8000, v106
	s_nop 0
	ds_write2_b32 v70, v98, v78 offset1:16
	v_add_u32_e32 v70, 0xc000, v106
	ds_write2_b32 v70, v102, v82 offset1:16
	v_add_u32_e32 v70, 0xec00, v68
	ds_write2_b32 v70, v91, v71 offset0:64 offset1:80
	v_add_u32_e32 v70, 0x4400, v106
	ds_write2_b32 v70, v87, v75 offset1:16
	v_add_u32_e32 v70, 0x8400, v106
	ds_write2_b32 v70, v99, v79 offset1:16
	v_add_u32_e32 v70, 0xc400, v106
	ds_write2_b32 v70, v103, v83 offset1:16
	v_add_u32_e32 v70, 0xf000, v68
	ds_write2_b32 v70, v92, v72 offset0:64 offset1:80
	v_add_u32_e32 v70, 0x4800, v106
	v_add_u32_e32 v68, 0xf400, v68
	ds_write2_b32 v70, v88, v76 offset1:16
	v_add_u32_e32 v70, 0x8800, v106
	ds_write2_b32 v68, v93, v73 offset0:64 offset1:80
	v_add_u32_e32 v68, 0x4c00, v106
	v_ashrrev_i32_e32 v90, 8, v139
	ds_write2_b32 v70, v100, v80 offset1:16
	ds_write2_b32 v68, v89, v77 offset1:16
	v_add_u32_e32 v68, 0x8c00, v106
	v_lshlrev_b32_e32 v80, 3, v90
	ds_write2_b32 v68, v101, v81 offset1:16
	v_add_u32_e32 v68, 0xcc00, v106
	v_ashrrev_i32_e32 v81, 31, v80
	v_add_u32_e32 v70, 0xc800, v106
	ds_write2_b32 v68, v105, v85 offset1:16
	v_lshlrev_b32_sdwa v68, v138, v139 dst_sel:DWORD dst_unused:UNUSED_PAD src0_sel:DWORD src1_sel:BYTE_0
	v_lshl_add_u64 v[118:119], v[80:81], 0, s[36:37]
	ds_write2_b32 v70, v104, v84 offset1:16
	v_lshl_add_u64 v[124:125], s[20:21], 0, v[68:69]
	v_lshlrev_b64 v[70:71], 9, v[118:119]
	v_lshl_add_u64 v[70:71], v[124:125], 0, v[70:71]
	s_waitcnt lgkmcnt(0)
	s_barrier
	global_load_ushort v81, v[70:71], off
	v_lshlrev_b32_e32 v70, 13, v90
	v_lshlrev_b32_sdwa v96, v17, v139 dst_sel:DWORD dst_unused:UNUSED_PAD src0_sel:DWORD src1_sel:BYTE_0
	v_add3_u32 v70, 0, v70, v96
	v_add_u32_e32 v72, 0xe900, v70
	ds_read2st64_b32 v[120:121], v70 offset0:233 offset1:237
	ds_read2st64_b32 v[84:85], v72 offset0:64 offset1:68
	ds_read2st64_b32 v[106:107], v72 offset0:128 offset1:132
	ds_read2st64_b32 v[112:113], v72 offset0:192 offset1:196
	ds_read2st64_b32 v[100:101], v70 offset0:241 offset1:245
	ds_read2st64_b32 v[86:87], v72 offset0:72 offset1:76
	ds_read2st64_b32 v[92:93], v72 offset0:136 offset1:140
	ds_read2st64_b32 v[94:95], v72 offset0:200 offset1:204
	ds_read2st64_b32 v[82:83], v70 offset0:249 offset1:253
	ds_read2st64_b32 v[88:89], v72 offset0:80 offset1:84
	ds_read2st64_b32 v[76:77], v72 offset0:144 offset1:148
	ds_read2st64_b32 v[78:79], v72 offset0:208 offset1:212
	ds_read2st64_b32 v[74:75], v72 offset0:24 offset1:28
	ds_read2st64_b32 v[144:145], v72 offset0:88 offset1:92
	s_waitcnt vmcnt(6) lgkmcnt(13)
	v_add_f32_e32 v70, v132, v120
	v_mul_f32_e32 v70, 0xbfb8aa3b, v70
	v_exp_f32_e32 v91, v70
	v_mul_i32_i24_e32 v90, 0x7080, v90
	v_add3_u32 v90, 0, v90, v96
	ds_read2st64_b32 v[70:71], v72 offset0:152 offset1:156
	ds_read2st64_b32 v[72:73], v72 offset0:216 offset1:220
	v_add_f32_e32 v91, 1.0, v91
	v_rcp_f32_e32 v91, v91
	ds_read2st64_b32 v[126:127], v90 offset1:4
	ds_read_b32 v120, v90 offset:2048
	s_waitcnt vmcnt(5) lgkmcnt(14)
	v_add_f32_e32 v84, v133, v84
	v_mul_f32_e32 v84, 0xbfb8aa3b, v84
	v_mul_f32_e32 v90, 0xbf1b4598, v91
	s_waitcnt vmcnt(1)
	v_add_f32_e32 v91, v137, v112
	v_mul_f32_e32 v91, 0xbfb8aa3b, v91
	v_exp_f32_e32 v84, v84
	v_exp_f32_e32 v91, v91
	v_mul_f32_e32 v90, 0x3fb8aa3b, v90
	v_exp_f32_e32 v156, v90
	v_add_f32_e32 v84, 1.0, v84
	v_add_f32_e32 v90, 1.0, v91
	v_rcp_f32_e32 v90, v90
	v_rcp_f32_e32 v143, v84
	s_waitcnt lgkmcnt(1)
	v_mul_f32_e32 v160, v134, v127
	v_mul_f32_e32 v162, v160, v160
	v_and_b32_e32 v68, 63, v139
	s_waitcnt vmcnt(0)
	v_lshlrev_b32_e32 v81, 16, v81
	s_waitcnt lgkmcnt(0)
	v_sub_f32_e32 v81, v81, v120
	v_fmac_f32_e32 v120, v81, v90
	v_add_f32_e32 v81, -1.0, v143
	v_fma_f32 v81, v135, v81, 1.0
	v_mul_f32_e32 v164, v81, v127
	v_add_f32_e32 v81, v133, v85
	v_mul_f32_e32 v81, 0xbfb8aa3b, v81
	v_exp_f32_e32 v81, v81
	v_or_b32_e32 v90, 1, v80
	v_mul_lo_u32 v84, v90, s61
	v_add3_u32 v141, 0, v84, v96
	v_add_f32_e32 v81, 1.0, v81
	v_rcp_f32_e32 v163, v81
	ds_read2st64_b32 v[122:123], v141 offset1:4
	v_ashrrev_i32_e32 v91, 31, v90
	v_lshl_add_u64 v[116:117], v[90:91], 0, s[36:37]
	v_add_f32_e32 v81, -1.0, v163
	v_fma_f32 v81, v135, v81, 1.0
	s_waitcnt lgkmcnt(0)
	v_mul_f32_e32 v161, v81, v123
	v_add_f32_e32 v81, v133, v86
	v_mul_f32_e32 v81, 0xbfb8aa3b, v81
	v_exp_f32_e32 v81, v81
	v_lshlrev_b64 v[84:85], 9, v[116:117]
	v_lshl_add_u64 v[148:149], v[124:125], 0, v[84:85]
	v_or_b32_e32 v84, 2, v80
	v_ashrrev_i32_e32 v85, 31, v84
	v_add_f32_e32 v81, 1.0, v81
	v_lshl_add_u64 v[110:111], v[84:85], 0, s[36:37]
	v_add_u32_e32 v84, 16, v141
	v_rcp_f32_e32 v179, v81
	ds_read2st64_b32 v[114:115], v84 offset0:14 offset1:18
	v_lshlrev_b64 v[84:85], 9, v[110:111]
	v_lshl_add_u64 v[150:151], v[124:125], 0, v[84:85]
	v_add_f32_e32 v81, -1.0, v179
	v_fma_f32 v81, v135, v81, 1.0
	s_waitcnt lgkmcnt(0)
	v_mul_f32_e32 v154, v81, v115
	v_add_f32_e32 v81, v133, v87
	v_mul_f32_e32 v81, 0xbfb8aa3b, v81
	v_exp_f32_e32 v81, v81
	v_or_b32_e32 v84, 3, v80
	v_ashrrev_i32_e32 v85, 31, v84
	v_lshl_add_u64 v[104:105], v[84:85], 0, s[36:37]
	v_add_f32_e32 v81, 1.0, v81
	v_add_u32_e32 v84, 32, v141
	v_rcp_f32_e32 v147, v81
	ds_read2st64_b32 v[108:109], v84 offset0:28 offset1:32
	v_lshlrev_b64 v[84:85], 9, v[104:105]
	v_lshl_add_u64 v[158:159], v[124:125], 0, v[84:85]
	v_add_f32_e32 v81, -1.0, v147
	v_fma_f32 v81, v135, v81, 1.0
	s_waitcnt lgkmcnt(0)
	v_mul_f32_e32 v146, v81, v109
	v_add_f32_e32 v81, v133, v88
	v_mul_f32_e32 v81, 0xbfb8aa3b, v81
	v_exp_f32_e32 v81, v81
	v_or_b32_e32 v84, 4, v80
	v_ashrrev_i32_e32 v85, 31, v84
	v_lshl_add_u64 v[98:99], v[84:85], 0, s[36:37]
	v_add_f32_e32 v81, 1.0, v81
	v_add_u32_e32 v84, 48, v141
	v_rcp_f32_e32 v183, v81
	ds_read2st64_b32 v[102:103], v84 offset0:42 offset1:46
	v_lshlrev_b64 v[84:85], 9, v[98:99]
	v_lshl_add_u64 v[166:167], v[124:125], 0, v[84:85]
	v_add_f32_e32 v81, -1.0, v183
	v_fma_f32 v81, v135, v81, 1.0
	s_waitcnt lgkmcnt(0)
	v_mul_f32_e32 v142, v81, v103
	v_add_f32_e32 v81, v133, v89
	v_mul_f32_e32 v81, 0xbfb8aa3b, v81
	v_exp_f32_e32 v81, v81
	v_or_b32_e32 v84, 5, v80
	v_ashrrev_i32_e32 v85, 31, v84
	v_lshl_add_u64 v[90:91], v[84:85], 0, s[36:37]
	v_add_f32_e32 v81, 1.0, v81
	v_add_u32_e32 v84, 64, v141
	v_rcp_f32_e32 v140, v81
	ds_read2st64_b32 v[96:97], v84 offset0:56 offset1:60
	v_mul_f32_e32 v176, v134, v123
	v_lshlrev_b64 v[84:85], 9, v[90:91]
	v_add_f32_e32 v81, -1.0, v140
	v_fma_f32 v81, v135, v81, 1.0
	s_waitcnt lgkmcnt(0)
	v_mul_f32_e32 v123, v81, v97
	v_add_f32_e32 v81, v133, v144
	v_mul_f32_e32 v81, 0xbfb8aa3b, v81
	v_exp_f32_e32 v81, v81
	v_lshl_add_u64 v[168:169], v[124:125], 0, v[84:85]
	v_or_b32_e32 v84, 6, v80
	v_ashrrev_i32_e32 v85, 31, v84
	v_add_f32_e32 v81, 1.0, v81
	v_lshl_add_u64 v[86:87], v[84:85], 0, s[36:37]
	v_add_u32_e32 v84, 0x50, v141
	v_rcp_f32_e32 v144, v81
	ds_read2st64_b32 v[88:89], v84 offset0:70 offset1:74
	v_mul_f32_e32 v181, v134, v109
	v_mul_f32_e32 v186, v134, v97
	v_add_f32_e32 v81, -1.0, v144
	v_fma_f32 v81, v135, v81, 1.0
	s_waitcnt lgkmcnt(0)
	v_mul_f32_e32 v188, v134, v89
	v_mul_f32_e32 v109, v81, v89
	v_add_f32_e32 v89, v133, v145
	v_mul_f32_e32 v89, 0xbfb8aa3b, v89
	v_exp_f32_e32 v97, v89
	v_or_b32_e32 v80, 7, v80
	v_ashrrev_i32_e32 v81, 31, v80
	v_lshlrev_b64 v[84:85], 9, v[86:87]
	v_lshl_add_u64 v[80:81], v[80:81], 0, s[36:37]
	v_mul_f32_e32 v177, v176, v176
	v_lshl_add_u64 v[170:171], v[124:125], 0, v[84:85]
	v_add_u32_e32 v84, 0x60, v141
	v_add_f32_e32 v97, 1.0, v97
	v_lshlrev_b64 v[172:173], 9, v[80:81]
	v_mul_f32_e32 v178, v134, v115
	v_mul_f32_e32 v185, v134, v103
	ds_read2st64_b32 v[84:85], v84 offset0:84 offset1:88
	ds_read_b32 v174, v141 offset:2048
	ds_read_b32 v165, v141 offset:5648
	ds_read_b32 v155, v141 offset:9248
	ds_read_b32 v145, v141 offset:12848
	ds_read_b32 v127, v141 offset:16448
	ds_read_b32 v112, v141 offset:20048
	ds_read_b32 v89, v141 offset:23648
	v_rcp_f32_e32 v103, v97
	v_lshl_add_u64 v[124:125], v[124:125], 0, v[172:173]
	global_load_ushort v175, v[148:149], off
	global_load_ushort v173, v[150:151], off
	global_load_ushort v157, v[158:159], off
	s_nop 0
	global_load_ushort v151, v[166:167], off
	global_load_ushort v141, v[168:169], off
	global_load_ushort v115, v[170:171], off
	global_load_ushort v97, v[124:125], off
	v_and_b32_e32 v149, 64, v153
	v_mov_b32_dpp v150, v162 quad_perm:[1,0,3,2] row_mask:0xf bank_mask:0xf bound_ctrl:1
	v_mov_b32_dpp v159, v177 quad_perm:[1,0,3,2] row_mask:0xf bank_mask:0xf bound_ctrl:1
	v_xor_b32_e32 v148, 16, v153
	v_add_u32_e32 v149, 64, v149
	v_fmac_f32_e32 v150, v160, v160
	v_fmac_f32_e32 v159, v176, v176
	v_cmp_lt_i32_e32 vcc, v148, v149
	v_add_f32_dpp v150, v150, v150 quad_perm:[2,3,0,1] row_mask:0xf bank_mask:0xf bound_ctrl:1
	v_add_f32_dpp v159, v159, v159 quad_perm:[2,3,0,1] row_mask:0xf bank_mask:0xf bound_ctrl:1
	v_cndmask_b32_e32 v148, v153, v148, vcc
	v_add_f32_dpp v150, v150, v150 row_half_mirror row_mask:0xf bank_mask:0xf bound_ctrl:1
	v_add_f32_dpp v159, v159, v159 row_half_mirror row_mask:0xf bank_mask:0xf bound_ctrl:1
	v_lshlrev_b32_e32 v166, 2, v148
	v_add_f32_dpp v150, v150, v150 row_mirror row_mask:0xf bank_mask:0xf bound_ctrl:1
	v_add_f32_dpp v159, v159, v159 row_mirror row_mask:0xf bank_mask:0xf bound_ctrl:1
	ds_bpermute_b32 v158, v166, v150
	ds_bpermute_b32 v162, v166, v159
	v_xor_b32_e32 v148, 32, v153
	v_cmp_lt_i32_e32 vcc, v148, v149
	v_mul_f32_e32 v180, v178, v178
	v_mul_f32_e32 v182, v181, v181
	v_cndmask_b32_e32 v148, v153, v148, vcc
	v_lshlrev_b32_e32 v167, 2, v148
	s_waitcnt lgkmcnt(1)
	v_add_f32_e32 v148, v150, v158
	s_waitcnt lgkmcnt(0)
	v_add_f32_e32 v150, v159, v162
	v_mov_b32_dpp v159, v180 quad_perm:[1,0,3,2] row_mask:0xf bank_mask:0xf bound_ctrl:1
	v_mov_b32_dpp v168, v182 quad_perm:[1,0,3,2] row_mask:0xf bank_mask:0xf bound_ctrl:1
	v_fmac_f32_e32 v159, v178, v178
	v_fmac_f32_e32 v168, v181, v181
	v_mul_f32_e32 v184, v185, v185
	v_add_f32_dpp v159, v159, v159 quad_perm:[2,3,0,1] row_mask:0xf bank_mask:0xf bound_ctrl:1
	v_add_f32_dpp v168, v168, v168 quad_perm:[2,3,0,1] row_mask:0xf bank_mask:0xf bound_ctrl:1
	v_mov_b32_dpp v170, v184 quad_perm:[1,0,3,2] row_mask:0xf bank_mask:0xf bound_ctrl:1
	v_add_f32_dpp v159, v159, v159 row_half_mirror row_mask:0xf bank_mask:0xf bound_ctrl:1
	v_add_f32_dpp v168, v168, v168 row_half_mirror row_mask:0xf bank_mask:0xf bound_ctrl:1
	v_fmac_f32_e32 v170, v185, v185
	v_add_f32_dpp v159, v159, v159 row_mirror row_mask:0xf bank_mask:0xf bound_ctrl:1
	v_add_f32_dpp v168, v168, v168 row_mirror row_mask:0xf bank_mask:0xf bound_ctrl:1
	ds_bpermute_b32 v162, v166, v159
	ds_bpermute_b32 v169, v166, v168
	v_add_f32_dpp v170, v170, v170 quad_perm:[2,3,0,1] row_mask:0xf bank_mask:0xf bound_ctrl:1
	ds_bpermute_b32 v149, v167, v148
	ds_bpermute_b32 v158, v167, v150
	v_add_f32_dpp v170, v170, v170 row_half_mirror row_mask:0xf bank_mask:0xf bound_ctrl:1
	s_waitcnt lgkmcnt(3)
	v_add_f32_e32 v159, v159, v162
	s_waitcnt lgkmcnt(2)
	v_add_f32_e32 v168, v168, v169
	v_add_f32_dpp v170, v170, v170 row_mirror row_mask:0xf bank_mask:0xf bound_ctrl:1
	ds_bpermute_b32 v171, v166, v170
	ds_bpermute_b32 v162, v167, v159
	ds_bpermute_b32 v169, v167, v168
	v_add_f32_e32 v125, -1.0, v103
	v_mul_f32_e32 v187, v186, v186
	v_mul_f32_e32 v189, v188, v188
	v_mul_f32_e32 v124, v134, v85
	v_fma_f32 v125, v135, v125, 1.0
	s_waitcnt lgkmcnt(2)
	v_add_f32_e32 v170, v170, v171
	v_mul_f32_e32 v85, v125, v85
	v_mul_f32_e32 v125, v124, v124
	ds_bpermute_b32 v171, v167, v170
	v_add_f32_e32 v148, v148, v149
	v_add_f32_e32 v149, v150, v158
	s_waitcnt lgkmcnt(2)
	v_add_f32_e32 v150, v159, v162
	s_waitcnt lgkmcnt(1)
	v_add_f32_e32 v158, v168, v169
	v_mov_b32_dpp v162, v187 quad_perm:[1,0,3,2] row_mask:0xf bank_mask:0xf bound_ctrl:1
	v_mov_b32_dpp v169, v189 quad_perm:[1,0,3,2] row_mask:0xf bank_mask:0xf bound_ctrl:1
	v_fmac_f32_e32 v162, v186, v186
	v_fmac_f32_e32 v169, v188, v188
	v_mov_b32_dpp v125, v125 quad_perm:[1,0,3,2] row_mask:0xf bank_mask:0xf bound_ctrl:1
	v_max_f32_e32 v148, 0x179abe15, v148
	v_add_f32_dpp v162, v162, v162 quad_perm:[2,3,0,1] row_mask:0xf bank_mask:0xf bound_ctrl:1
	v_add_f32_dpp v169, v169, v169 quad_perm:[2,3,0,1] row_mask:0xf bank_mask:0xf bound_ctrl:1
	v_fmac_f32_e32 v125, v124, v124
	v_rsq_f32_e32 v148, v148
	v_add_f32_dpp v162, v162, v162 row_half_mirror row_mask:0xf bank_mask:0xf bound_ctrl:1
	v_add_f32_dpp v169, v169, v169 row_half_mirror row_mask:0xf bank_mask:0xf bound_ctrl:1
	v_add_f32_dpp v125, v125, v125 quad_perm:[2,3,0,1] row_mask:0xf bank_mask:0xf bound_ctrl:1
	v_add_f32_dpp v162, v162, v162 row_mirror row_mask:0xf bank_mask:0xf bound_ctrl:1
	v_add_f32_dpp v169, v169, v169 row_mirror row_mask:0xf bank_mask:0xf bound_ctrl:1
	v_add_f32_dpp v125, v125, v125 row_half_mirror row_mask:0xf bank_mask:0xf bound_ctrl:1
	s_waitcnt lgkmcnt(0)
	v_add_f32_e32 v159, v170, v171
	ds_bpermute_b32 v168, v166, v162
	ds_bpermute_b32 v170, v166, v169
	v_add_f32_dpp v125, v125, v125 row_mirror row_mask:0xf bank_mask:0xf bound_ctrl:1
	ds_bpermute_b32 v171, v166, v125
	v_mul_f32_e32 v189, v160, v148
	v_mul_f32_e32 v203, v143, v189
	v_max_f32_e32 v143, 0x179abe15, v149
	v_max_f32_e32 v150, 0x179abe15, v150
	v_rsq_f32_e32 v143, v143
	v_rsq_f32_e32 v150, v150
	s_waitcnt lgkmcnt(2)
	v_add_f32_e32 v162, v162, v168
	s_waitcnt lgkmcnt(1)
	v_add_f32_e32 v169, v169, v170
	ds_bpermute_b32 v168, v167, v162
	ds_bpermute_b32 v170, v167, v169
	s_waitcnt lgkmcnt(2)
	v_add_f32_e32 v125, v125, v171
	ds_bpermute_b32 v171, v167, v125
	v_mul_f32_e32 v190, v176, v143
	v_mul_f32_e32 v178, v178, v150
	v_max_f32_e32 v143, 0x179abe15, v158
	v_max_f32_e32 v150, 0x179abe15, v159
	v_rsq_f32_e32 v143, v143
	v_rsq_f32_e32 v150, v150
	s_waitcnt lgkmcnt(2)
	v_add_f32_e32 v162, v162, v168
	s_waitcnt lgkmcnt(1)
	v_add_f32_e32 v169, v169, v170
	s_waitcnt lgkmcnt(0)
	v_add_f32_e32 v125, v125, v171
	v_mul_f32_e32 v184, v179, v178
	v_mul_f32_e32 v179, v181, v143
	v_mul_f32_e32 v158, v185, v150
	v_max_f32_e32 v143, 0x179abe15, v162
	v_max_f32_e32 v150, 0x179abe15, v169
	v_rsq_f32_e32 v143, v143
	v_rsq_f32_e32 v150, v150
	v_max_f32_e32 v125, 0x179abe15, v125
	v_rsq_f32_e32 v125, v125
	v_mul_f32_e32 v148, v126, v164
	v_mul_f32_e32 v149, v136, v148
	v_mul_f32_e32 v162, v186, v143
	v_mul_f32_e32 v143, v188, v150
	v_mul_f32_e32 v150, v144, v143
	v_mul_f32_e32 v144, v124, v125
	v_mov_b32_dpp v124, v149 quad_perm:[1,0,3,2] row_mask:0xf bank_mask:0xf bound_ctrl:1
	v_fmac_f32_e32 v124, v136, v148
	v_mul_f32_e32 v160, v122, v161
	v_mul_f32_e32 v170, v136, v160
	v_add_f32_dpp v124, v124, v124 quad_perm:[2,3,0,1] row_mask:0xf bank_mask:0xf bound_ctrl:1
	v_mul_f32_e32 v171, v114, v154
	v_mul_f32_e32 v172, v136, v171
	v_add_f32_dpp v124, v124, v124 row_half_mirror row_mask:0xf bank_mask:0xf bound_ctrl:1
	v_mov_b32_dpp v148, v170 quad_perm:[1,0,3,2] row_mask:0xf bank_mask:0xf bound_ctrl:1
	v_fmac_f32_e32 v148, v136, v160
	v_add_f32_dpp v124, v124, v124 row_mirror row_mask:0xf bank_mask:0xf bound_ctrl:1
	ds_bpermute_b32 v125, v166, v124
	v_add_f32_dpp v148, v148, v148 quad_perm:[2,3,0,1] row_mask:0xf bank_mask:0xf bound_ctrl:1
	v_mul_f32_e32 v159, v108, v146
	v_mul_f32_e32 v176, v136, v159
	v_add_f32_dpp v148, v148, v148 row_half_mirror row_mask:0xf bank_mask:0xf bound_ctrl:1
	s_waitcnt lgkmcnt(0)
	v_add_f32_e32 v197, v124, v125
	v_mov_b32_dpp v124, v172 quad_perm:[1,0,3,2] row_mask:0xf bank_mask:0xf bound_ctrl:1
	v_fmac_f32_e32 v124, v136, v171
	v_add_f32_dpp v148, v148, v148 row_mirror row_mask:0xf bank_mask:0xf bound_ctrl:1
	ds_bpermute_b32 v149, v166, v148
	v_add_f32_dpp v124, v124, v124 quad_perm:[2,3,0,1] row_mask:0xf bank_mask:0xf bound_ctrl:1
	v_mul_f32_e32 v177, v102, v142
	v_mul_f32_e32 v169, v96, v123
	v_add_f32_dpp v124, v124, v124 row_half_mirror row_mask:0xf bank_mask:0xf bound_ctrl:1
	v_mul_f32_e32 v180, v136, v177
	v_mul_f32_e32 v182, v136, v169
	v_add_f32_dpp v124, v124, v124 row_mirror row_mask:0xf bank_mask:0xf bound_ctrl:1
	ds_bpermute_b32 v125, v166, v124
	s_waitcnt lgkmcnt(1)
	v_add_f32_e32 v191, v148, v149
	v_mov_b32_dpp v148, v176 quad_perm:[1,0,3,2] row_mask:0xf bank_mask:0xf bound_ctrl:1
	v_fmac_f32_e32 v148, v136, v159
	v_mov_b32_dpp v159, v180 quad_perm:[1,0,3,2] row_mask:0xf bank_mask:0xf bound_ctrl:1
	s_waitcnt lgkmcnt(0)
	v_add_f32_e32 v187, v124, v125
	v_mov_b32_dpp v124, v182 quad_perm:[1,0,3,2] row_mask:0xf bank_mask:0xf bound_ctrl:1
	v_fmac_f32_e32 v159, v136, v177
	v_fmac_f32_e32 v124, v136, v169
	v_add_f32_dpp v148, v148, v148 quad_perm:[2,3,0,1] row_mask:0xf bank_mask:0xf bound_ctrl:1
	v_add_f32_dpp v159, v159, v159 quad_perm:[2,3,0,1] row_mask:0xf bank_mask:0xf bound_ctrl:1
	v_add_f32_dpp v124, v124, v124 quad_perm:[2,3,0,1] row_mask:0xf bank_mask:0xf bound_ctrl:1
	v_add_f32_dpp v148, v148, v148 row_half_mirror row_mask:0xf bank_mask:0xf bound_ctrl:1
	v_add_f32_dpp v159, v159, v159 row_half_mirror row_mask:0xf bank_mask:0xf bound_ctrl:1
	v_add_f32_dpp v124, v124, v124 row_half_mirror row_mask:0xf bank_mask:0xf bound_ctrl:1
	v_add_f32_dpp v148, v148, v148 row_mirror row_mask:0xf bank_mask:0xf bound_ctrl:1
	v_add_f32_dpp v159, v159, v159 row_mirror row_mask:0xf bank_mask:0xf bound_ctrl:1
	v_add_f32_dpp v124, v124, v124 row_mirror row_mask:0xf bank_mask:0xf bound_ctrl:1
	ds_bpermute_b32 v149, v166, v148
	ds_bpermute_b32 v171, v166, v159
	ds_bpermute_b32 v125, v166, v124
	v_mul_f32_e32 v168, v183, v158
	v_mul_f32_e32 v183, v88, v109
	v_mul_f32_e32 v160, v84, v85
	v_mul_f32_e32 v185, v136, v183
	v_mul_f32_e32 v170, v136, v160
	s_waitcnt lgkmcnt(2)
	v_add_f32_e32 v180, v148, v149
	s_waitcnt lgkmcnt(1)
	v_add_f32_e32 v176, v159, v171
	v_mov_b32_dpp v148, v185 quad_perm:[1,0,3,2] row_mask:0xf bank_mask:0xf bound_ctrl:1
	v_mov_b32_dpp v159, v170 quad_perm:[1,0,3,2] row_mask:0xf bank_mask:0xf bound_ctrl:1
	s_waitcnt lgkmcnt(0)
	v_add_f32_e32 v169, v124, v125
	v_mul_f32_e32 v124, v203, v190
	v_fmac_f32_e32 v148, v136, v183
	v_fmac_f32_e32 v159, v136, v160
	v_mov_b32_dpp v124, v124 quad_perm:[1,0,3,2] row_mask:0xf bank_mask:0xf bound_ctrl:1
	v_add_f32_dpp v148, v148, v148 quad_perm:[2,3,0,1] row_mask:0xf bank_mask:0xf bound_ctrl:1
	v_add_f32_dpp v159, v159, v159 quad_perm:[2,3,0,1] row_mask:0xf bank_mask:0xf bound_ctrl:1
	v_fmac_f32_e32 v124, v203, v190
	v_add_f32_dpp v148, v148, v148 row_half_mirror row_mask:0xf bank_mask:0xf bound_ctrl:1
	v_add_f32_dpp v159, v159, v159 row_half_mirror row_mask:0xf bank_mask:0xf bound_ctrl:1
	v_add_f32_dpp v124, v124, v124 quad_perm:[2,3,0,1] row_mask:0xf bank_mask:0xf bound_ctrl:1
	v_add_f32_dpp v148, v148, v148 row_mirror row_mask:0xf bank_mask:0xf bound_ctrl:1
	v_add_f32_dpp v171, v159, v159 row_mirror row_mask:0xf bank_mask:0xf bound_ctrl:1
	v_add_f32_dpp v124, v124, v124 row_half_mirror row_mask:0xf bank_mask:0xf bound_ctrl:1
	ds_bpermute_b32 v149, v166, v148
	ds_bpermute_b32 v172, v166, v171
	v_mul_f32_e32 v125, v164, v190
	v_add_f32_dpp v124, v124, v124 row_mirror row_mask:0xf bank_mask:0xf bound_ctrl:1
	ds_bpermute_b32 v185, v166, v124
	v_mov_b32_dpp v125, v125 quad_perm:[1,0,3,2] row_mask:0xf bank_mask:0xf bound_ctrl:1
	v_fmac_f32_e32 v125, v164, v190
	s_waitcnt lgkmcnt(2)
	v_add_f32_e32 v159, v148, v149
	s_waitcnt lgkmcnt(1)
	v_add_f32_e32 v148, v171, v172
	v_add_f32_dpp v125, v125, v125 quad_perm:[2,3,0,1] row_mask:0xf bank_mask:0xf bound_ctrl:1
	v_mul_f32_e32 v171, v184, v179
	v_mul_f32_e32 v172, v154, v179
	v_add_f32_dpp v125, v125, v125 row_half_mirror row_mask:0xf bank_mask:0xf bound_ctrl:1
	v_mul_f32_e32 v182, v168, v162
	s_waitcnt lgkmcnt(0)
	v_add_f32_e32 v201, v124, v185
	v_add_f32_dpp v125, v125, v125 row_mirror row_mask:0xf bank_mask:0xf bound_ctrl:1
	ds_bpermute_b32 v186, v166, v125
	v_mov_b32_dpp v124, v171 quad_perm:[1,0,3,2] row_mask:0xf bank_mask:0xf bound_ctrl:1
	v_mov_b32_dpp v171, v172 quad_perm:[1,0,3,2] row_mask:0xf bank_mask:0xf bound_ctrl:1
	v_mov_b32_dpp v182, v182 quad_perm:[1,0,3,2] row_mask:0xf bank_mask:0xf bound_ctrl:1
	v_fmac_f32_e32 v124, v184, v179
	v_fmac_f32_e32 v171, v154, v179
	v_fmac_f32_e32 v182, v168, v162
	v_add_f32_dpp v124, v124, v124 quad_perm:[2,3,0,1] row_mask:0xf bank_mask:0xf bound_ctrl:1
	v_add_f32_dpp v171, v171, v171 quad_perm:[2,3,0,1] row_mask:0xf bank_mask:0xf bound_ctrl:1
	v_add_f32_dpp v182, v182, v182 quad_perm:[2,3,0,1] row_mask:0xf bank_mask:0xf bound_ctrl:1
	v_add_f32_dpp v124, v124, v124 row_half_mirror row_mask:0xf bank_mask:0xf bound_ctrl:1
	v_add_f32_dpp v171, v171, v171 row_half_mirror row_mask:0xf bank_mask:0xf bound_ctrl:1
	v_add_f32_dpp v182, v182, v182 row_half_mirror row_mask:0xf bank_mask:0xf bound_ctrl:1
	v_add_f32_dpp v124, v124, v124 row_mirror row_mask:0xf bank_mask:0xf bound_ctrl:1
	v_add_f32_dpp v171, v171, v171 row_mirror row_mask:0xf bank_mask:0xf bound_ctrl:1
	v_add_f32_dpp v182, v182, v182 row_mirror row_mask:0xf bank_mask:0xf bound_ctrl:1
	s_waitcnt lgkmcnt(0)
	v_add_f32_e32 v199, v125, v186
	ds_bpermute_b32 v125, v166, v124
	ds_bpermute_b32 v172, v166, v171
	ds_bpermute_b32 v185, v166, v182
	v_mul_f32_e32 v183, v142, v162
	v_mul_f32_e32 v204, v150, v144
	v_mul_f32_e32 v205, v109, v144
	s_waitcnt lgkmcnt(2)
	v_add_f32_e32 v195, v124, v125
	s_waitcnt lgkmcnt(1)
	v_add_f32_e32 v193, v171, v172
	s_waitcnt lgkmcnt(0)
	v_add_f32_e32 v185, v182, v185
	v_mov_b32_dpp v124, v183 quad_perm:[1,0,3,2] row_mask:0xf bank_mask:0xf bound_ctrl:1
	v_mov_b32_dpp v171, v204 quad_perm:[1,0,3,2] row_mask:0xf bank_mask:0xf bound_ctrl:1
	v_mov_b32_dpp v182, v205 quad_perm:[1,0,3,2] row_mask:0xf bank_mask:0xf bound_ctrl:1
	v_fmac_f32_e32 v124, v142, v162
	v_fmac_f32_e32 v171, v150, v144
	v_fmac_f32_e32 v182, v109, v144
	v_add_f32_dpp v124, v124, v124 quad_perm:[2,3,0,1] row_mask:0xf bank_mask:0xf bound_ctrl:1
	v_add_f32_dpp v171, v171, v171 quad_perm:[2,3,0,1] row_mask:0xf bank_mask:0xf bound_ctrl:1
	v_add_f32_dpp v182, v182, v182 quad_perm:[2,3,0,1] row_mask:0xf bank_mask:0xf bound_ctrl:1
	v_add_f32_dpp v124, v124, v124 row_half_mirror row_mask:0xf bank_mask:0xf bound_ctrl:1
	v_add_f32_dpp v171, v171, v171 row_half_mirror row_mask:0xf bank_mask:0xf bound_ctrl:1
	v_add_f32_dpp v182, v182, v182 row_half_mirror row_mask:0xf bank_mask:0xf bound_ctrl:1
	v_add_f32_dpp v124, v124, v124 row_mirror row_mask:0xf bank_mask:0xf bound_ctrl:1
	v_add_f32_dpp v171, v171, v171 row_mirror row_mask:0xf bank_mask:0xf bound_ctrl:1
	v_add_f32_dpp v204, v182, v182 row_mirror row_mask:0xf bank_mask:0xf bound_ctrl:1
	ds_bpermute_b32 v125, v166, v124
	ds_bpermute_b32 v172, v166, v171
	ds_bpermute_b32 v166, v166, v204
	ds_bpermute_b32 v198, v167, v197
	ds_bpermute_b32 v192, v167, v191
	s_waitcnt lgkmcnt(4)
	v_add_f32_e32 v182, v124, v125
	s_waitcnt lgkmcnt(3)
	v_add_f32_e32 v171, v171, v172
	s_waitcnt lgkmcnt(2)
	v_add_f32_e32 v166, v204, v166
	v_lshlrev_b64 v[204:205], 8, v[118:119]
	v_or_b32_sdwa v204, v204, v139 dst_sel:DWORD dst_unused:UNUSED_PAD src0_sel:DWORD src1_sel:BYTE_0
	v_lshl_add_u64 v[206:207], v[204:205], 2, s[14:15]
	v_lshlrev_b64 v[204:205], 1, v[204:205]
	ds_bpermute_b32 v188, v167, v187
	ds_bpermute_b32 v181, v167, v180
	ds_bpermute_b32 v177, v167, v176
	ds_bpermute_b32 v170, v167, v169
	ds_bpermute_b32 v160, v167, v159
	ds_bpermute_b32 v149, v167, v148
	ds_bpermute_b32 v202, v167, v201
	ds_bpermute_b32 v200, v167, v199
	ds_bpermute_b32 v196, v167, v195
	ds_bpermute_b32 v194, v167, v193
	ds_bpermute_b32 v186, v167, v185
	ds_bpermute_b32 v183, v167, v182
	ds_bpermute_b32 v172, v167, v171
	ds_bpermute_b32 v167, v167, v166
	global_store_dword v[206:207], v156, off
	v_cvt_pk_bf16_f32 v126, v126, v69

	global_store_short v204, v126, s[26:27]
	v_cvt_pk_bf16_f32 v126, v164, v69

	v_bfe_u32 v124, v139, 6, 2
	global_store_short v204, v126, s[28:29]
	v_cvt_pk_bf16_f32 v126, v203, v69

	v_cmp_eq_u32_e32 vcc, 0, v68
	v_lshlrev_b32_e32 v68, 2, v124
	global_store_short v204, v126, s[30:31]
	v_xor_b32_e32 v126, 0x80000000, v189

	v_lshl_add_u64 v[124:125], s[22:23], 0, v[68:69]
	v_cvt_pk_bf16_f32 v126, v126, v69
	global_store_short v204, v126, s[34:35]
	v_lshl_add_u64 v[206:207], s[16:17], 0, v[204:205]

	v_cvt_pk_bf16_f32 v120, v120, v69
	global_store_short v[206:207], v120, off
	v_cvt_pk_bf16_f32 v106, v106, v69
	global_store_short v204, v106, s[18:19]
	s_and_saveexec_b64 s[4:5], vcc

	s_waitcnt lgkmcnt(14)
	v_add_f32_e32 v106, v197, v198
	v_lshl_add_u64 v[118:119], v[118:119], 4, v[124:125]
	global_store_dword v[118:119], v106, off
.LBB0_1185:
	s_or_b64 exec, exec, s[4:5]
	v_add_f32_e32 v106, v132, v121
	v_mul_f32_e32 v106, 0xbfb8aa3b, v106
	v_exp_f32_e32 v106, v106
	v_lshl_add_u64 v[118:119], s[24:25], 0, v[68:69]
	v_lshlrev_b64 v[120:121], 8, v[116:117]
	v_or_b32_sdwa v120, v120, v139 dst_sel:DWORD dst_unused:UNUSED_PAD src0_sel:DWORD src1_sel:BYTE_0
	v_add_f32_e32 v106, 1.0, v106
	v_rcp_f32_e32 v106, v106
	v_mul_f32_e32 v126, v163, v190
	s_waitcnt lgkmcnt(7)
	v_add_f32_e32 v163, v201, v202
	v_lshl_add_u64 v[202:203], v[120:121], 2, s[14:15]
	v_mul_f32_e32 v68, 0xbf1b4598, v106
	v_mul_f32_e32 v68, 0x3fb8aa3b, v68
	v_exp_f32_e32 v68, v68
	v_lshlrev_b64 v[120:121], 1, v[120:121]

	global_store_dword v[202:203], v68, off
	v_cvt_pk_bf16_f32 v68, v122, v69
	global_store_short v120, v68, s[26:27]
	v_cvt_pk_bf16_f32 v68, v161, v69

	global_store_short v120, v68, s[28:29]
	v_cvt_pk_bf16_f32 v68, v126, v69

	global_store_short v120, v68, s[30:31]
	v_mul_f32_e32 v68, v156, v190
	v_fma_f32 v68, v189, v163, -v68

	v_cvt_pk_bf16_f32 v68, v68, v69
	global_store_short v120, v68, s[34:35]
	s_and_saveexec_b64 s[4:5], vcc

	s_waitcnt lgkmcnt(6)
	v_add_f32_e32 v68, v199, v200
	v_lshl_add_u64 v[198:199], v[116:117], 4, v[118:119]
	v_xor_b32_e32 v68, 0x80000000, v68
	global_store_dword v[198:199], v68, off
.LBB0_1187:
	s_or_b64 exec, exec, s[4:5]
	v_add_f32_e32 v68, v137, v113
	v_mul_f32_e32 v68, 0xbfb8aa3b, v68
	v_exp_f32_e32 v68, v68
	s_waitcnt vmcnt(18)
	v_lshlrev_b32_e32 v106, 16, v175
	v_sub_f32_e32 v106, v106, v174

	v_add_f32_e32 v68, 1.0, v68
	v_rcp_f32_e32 v68, v68
	s_nop 0
	v_fmac_f32_e32 v174, v68, v106
	v_cvt_pk_bf16_f32 v68, v174, v69
	global_store_short v120, v68, s[16:17]
	v_cvt_pk_bf16_f32 v68, v107, v69

	global_store_short v120, v68, s[18:19]
	s_and_saveexec_b64 s[4:5], vcc

	v_add_f32_e32 v68, v191, v192
	v_lshl_add_u64 v[106:107], v[116:117], 4, v[124:125]
	global_store_dword v[106:107], v68, off
.LBB0_1189:
	s_or_b64 exec, exec, s[4:5]
	v_add_f32_e32 v68, v132, v100
	v_mul_f32_e32 v68, 0xbfb8aa3b, v68
	v_exp_f32_e32 v68, v68
	v_add_f32_e32 v94, v137, v94
	v_mul_f32_e32 v94, 0xbfb8aa3b, v94
	v_exp_f32_e32 v94, v94
	v_add_f32_e32 v68, 1.0, v68
	v_rcp_f32_e32 v68, v68
	v_lshlrev_b64 v[106:107], 8, v[110:111]
	v_add_f32_e32 v94, 1.0, v94
	v_rcp_f32_e32 v94, v94
	v_mul_f32_e32 v68, 0xbf1b4598, v68
	v_mul_f32_e32 v68, 0x3fb8aa3b, v68
	v_exp_f32_e32 v68, v68
	s_waitcnt vmcnt(19)
	v_lshlrev_b32_e32 v100, 16, v173
	v_or_b32_sdwa v106, v106, v139 dst_sel:DWORD dst_unused:UNUSED_PAD src0_sel:DWORD src1_sel:BYTE_0
	v_sub_f32_e32 v100, v100, v165
	v_lshl_add_u64 v[116:117], v[106:107], 2, s[14:15]
	v_lshlrev_b64 v[106:107], 1, v[106:107]
	v_fmac_f32_e32 v165, v94, v100
	global_store_dword v[116:117], v68, off
	v_cvt_pk_bf16_f32 v94, v114, v69

	global_store_short v106, v94, s[26:27]
	v_cvt_pk_bf16_f32 v94, v154, v69

	global_store_short v106, v94, s[28:29]
	v_cvt_pk_bf16_f32 v94, v184, v69

	global_store_short v106, v94, s[30:31]
	v_xor_b32_e32 v94, 0x80000000, v178

	v_cvt_pk_bf16_f32 v94, v94, v69
	global_store_short v106, v94, s[34:35]
	v_lshl_add_u64 v[116:117], s[16:17], 0, v[106:107]

	v_cvt_pk_bf16_f32 v94, v165, v69
	global_store_short v[116:117], v94, off
	v_cvt_pk_bf16_f32 v92, v92, v69
	global_store_short v106, v92, s[18:19]
	s_and_saveexec_b64 s[4:5], vcc

	v_add_f32_e32 v92, v187, v188
	v_lshl_add_u64 v[106:107], v[110:111], 4, v[124:125]
	global_store_dword v[106:107], v92, off
.LBB0_1191:
	s_or_b64 exec, exec, s[4:5]
	v_add_f32_e32 v92, v132, v101
	v_mul_f32_e32 v92, 0xbfb8aa3b, v92
	v_exp_f32_e32 v92, v92
	v_lshlrev_b64 v[100:101], 8, v[104:105]
	v_or_b32_sdwa v100, v100, v139 dst_sel:DWORD dst_unused:UNUSED_PAD src0_sel:DWORD src1_sel:BYTE_0
	v_lshl_add_u64 v[106:107], v[100:101], 2, s[14:15]
	v_add_f32_e32 v92, 1.0, v92
	v_rcp_f32_e32 v92, v92
	v_lshlrev_b64 v[100:101], 1, v[100:101]

	s_waitcnt lgkmcnt(5)
	v_add_f32_e32 v113, v195, v196
	v_mul_f32_e32 v92, 0xbf1b4598, v92
	v_mul_f32_e32 v92, 0x3fb8aa3b, v92
	v_exp_f32_e32 v92, v92
	v_mul_f32_e32 v68, v68, v179
	v_mul_f32_e32 v94, v147, v179
	v_fma_f32 v68, v178, v113, -v68
	global_store_dword v[106:107], v92, off
	v_cvt_pk_bf16_f32 v92, v108, v69

	global_store_short v100, v92, s[26:27]
	v_cvt_pk_bf16_f32 v92, v146, v69
	global_store_short v100, v92, s[28:29]

	v_cvt_pk_bf16_f32 v92, v94, v69
	global_store_short v100, v92, s[30:31]

	v_cvt_pk_bf16_f32 v68, v68, v69
	global_store_short v100, v68, s[34:35]
	s_and_saveexec_b64 s[4:5], vcc

	s_waitcnt lgkmcnt(4)
	v_add_f32_e32 v68, v193, v194
	v_lshl_add_u64 v[106:107], v[104:105], 4, v[118:119]
	v_xor_b32_e32 v68, 0x80000000, v68
	global_store_dword v[106:107], v68, off
.LBB0_1193:
	s_or_b64 exec, exec, s[4:5]
	v_add_f32_e32 v68, v137, v95
	v_mul_f32_e32 v68, 0xbfb8aa3b, v68
	v_exp_f32_e32 v68, v68
	s_waitcnt vmcnt(30)
	v_lshlrev_b32_e32 v92, 16, v157
	v_sub_f32_e32 v92, v92, v155

	v_add_f32_e32 v68, 1.0, v68
	v_rcp_f32_e32 v68, v68
	s_nop 0
	v_fmac_f32_e32 v155, v68, v92
	v_cvt_pk_bf16_f32 v68, v155, v69
	global_store_short v100, v68, s[16:17]
	v_cvt_pk_bf16_f32 v68, v93, v69

	global_store_short v100, v68, s[18:19]
	s_and_saveexec_b64 s[4:5], vcc

	v_add_f32_e32 v68, v180, v181
	v_lshl_add_u64 v[92:93], v[104:105], 4, v[124:125]
	global_store_dword v[92:93], v68, off
.LBB0_1195:
	s_or_b64 exec, exec, s[4:5]
	v_add_f32_e32 v68, v132, v82
	v_mul_f32_e32 v68, 0xbfb8aa3b, v68
	v_exp_f32_e32 v68, v68
	v_add_f32_e32 v78, v137, v78
	v_mul_f32_e32 v78, 0xbfb8aa3b, v78
	v_exp_f32_e32 v78, v78
	v_add_f32_e32 v68, 1.0, v68
	v_rcp_f32_e32 v68, v68
	v_lshlrev_b64 v[92:93], 8, v[98:99]
	v_add_f32_e32 v78, 1.0, v78
	v_rcp_f32_e32 v78, v78
	v_mul_f32_e32 v68, 0xbf1b4598, v68
	v_mul_f32_e32 v68, 0x3fb8aa3b, v68
	v_exp_f32_e32 v68, v68
	s_waitcnt vmcnt(31)
	v_lshlrev_b32_e32 v82, 16, v151
	v_or_b32_sdwa v92, v92, v139 dst_sel:DWORD dst_unused:UNUSED_PAD src0_sel:DWORD src1_sel:BYTE_0
	v_sub_f32_e32 v82, v82, v145
	v_lshl_add_u64 v[94:95], v[92:93], 2, s[14:15]
	v_lshlrev_b64 v[92:93], 1, v[92:93]
	v_fmac_f32_e32 v145, v78, v82
	global_store_dword v[94:95], v68, off
	v_cvt_pk_bf16_f32 v78, v102, v69

	global_store_short v92, v78, s[26:27]
	v_cvt_pk_bf16_f32 v78, v142, v69

	global_store_short v92, v78, s[28:29]
	v_cvt_pk_bf16_f32 v78, v168, v69

	global_store_short v92, v78, s[30:31]
	v_xor_b32_e32 v78, 0x80000000, v158

	v_cvt_pk_bf16_f32 v78, v78, v69
	global_store_short v92, v78, s[34:35]
	v_lshl_add_u64 v[94:95], s[16:17], 0, v[92:93]

	v_cvt_pk_bf16_f32 v78, v145, v69
	global_store_short v[94:95], v78, off
	v_cvt_pk_bf16_f32 v76, v76, v69
	global_store_short v92, v76, s[18:19]
	s_and_saveexec_b64 s[4:5], vcc

	v_add_f32_e32 v76, v176, v177
	v_lshl_add_u64 v[92:93], v[98:99], 4, v[124:125]
	global_store_dword v[92:93], v76, off
.LBB0_1197:
	s_or_b64 exec, exec, s[4:5]
	v_add_f32_e32 v76, v132, v83
	v_mul_f32_e32 v76, 0xbfb8aa3b, v76
	v_exp_f32_e32 v76, v76
	v_lshlrev_b64 v[82:83], 8, v[90:91]
	v_or_b32_sdwa v82, v82, v139 dst_sel:DWORD dst_unused:UNUSED_PAD src0_sel:DWORD src1_sel:BYTE_0
	v_lshl_add_u64 v[92:93], v[82:83], 2, s[14:15]
	v_add_f32_e32 v76, 1.0, v76
	v_rcp_f32_e32 v76, v76
	v_lshlrev_b64 v[82:83], 1, v[82:83]

	s_waitcnt lgkmcnt(3)
	v_add_f32_e32 v98, v185, v186
	v_mul_f32_e32 v76, 0xbf1b4598, v76
	v_mul_f32_e32 v76, 0x3fb8aa3b, v76
	v_exp_f32_e32 v76, v76
	v_mul_f32_e32 v68, v68, v162
	v_mul_f32_e32 v78, v140, v162
	v_fma_f32 v68, v158, v98, -v68
	global_store_dword v[92:93], v76, off
	v_cvt_pk_bf16_f32 v76, v96, v69

	global_store_short v82, v76, s[26:27]
	v_cvt_pk_bf16_f32 v76, v123, v69
	global_store_short v82, v76, s[28:29]

	v_cvt_pk_bf16_f32 v76, v78, v69
	global_store_short v82, v76, s[30:31]

	v_cvt_pk_bf16_f32 v68, v68, v69
	global_store_short v82, v68, s[34:35]
	s_and_saveexec_b64 s[4:5], vcc

	s_waitcnt lgkmcnt(2)
	v_add_f32_e32 v68, v182, v183
	v_lshl_add_u64 v[92:93], v[90:91], 4, v[118:119]
	v_xor_b32_e32 v68, 0x80000000, v68
	global_store_dword v[92:93], v68, off
.LBB0_1199:
	s_or_b64 exec, exec, s[4:5]
	v_add_f32_e32 v68, v137, v79
	v_mul_f32_e32 v68, 0xbfb8aa3b, v68
	v_exp_f32_e32 v68, v68
	s_waitcnt vmcnt(42)
	v_lshlrev_b32_e32 v76, 16, v141
	v_sub_f32_e32 v76, v76, v127

	v_add_f32_e32 v68, 1.0, v68
	v_rcp_f32_e32 v68, v68
	s_nop 0
	v_fmac_f32_e32 v127, v68, v76
	v_cvt_pk_bf16_f32 v68, v127, v69
	global_store_short v82, v68, s[16:17]
	v_cvt_pk_bf16_f32 v68, v77, v69

	global_store_short v82, v68, s[18:19]
	s_and_saveexec_b64 s[4:5], vcc

	v_add_f32_e32 v68, v169, v170
	v_lshl_add_u64 v[76:77], v[90:91], 4, v[124:125]
	global_store_dword v[76:77], v68, off
.LBB0_1201:
	s_or_b64 exec, exec, s[4:5]
	v_add_f32_e32 v68, v132, v74
	v_mul_f32_e32 v68, 0xbfb8aa3b, v68
	v_exp_f32_e32 v68, v68
	v_add_f32_e32 v72, v137, v72
	v_mul_f32_e32 v72, 0xbfb8aa3b, v72
	v_exp_f32_e32 v72, v72
	v_add_f32_e32 v68, 1.0, v68
	v_rcp_f32_e32 v68, v68
	v_lshlrev_b64 v[76:77], 8, v[86:87]
	v_add_f32_e32 v72, 1.0, v72
	v_rcp_f32_e32 v72, v72
	v_mul_f32_e32 v68, 0xbf1b4598, v68
	v_mul_f32_e32 v68, 0x3fb8aa3b, v68
	v_exp_f32_e32 v68, v68
	s_waitcnt vmcnt(43)
	v_lshlrev_b32_e32 v74, 16, v115
	v_or_b32_sdwa v76, v76, v139 dst_sel:DWORD dst_unused:UNUSED_PAD src0_sel:DWORD src1_sel:BYTE_0
	v_sub_f32_e32 v74, v74, v112
	v_lshl_add_u64 v[78:79], v[76:77], 2, s[14:15]
	v_lshlrev_b64 v[76:77], 1, v[76:77]
	v_fmac_f32_e32 v112, v72, v74
	global_store_dword v[78:79], v68, off
	v_cvt_pk_bf16_f32 v72, v88, v69

	global_store_short v76, v72, s[26:27]
	v_cvt_pk_bf16_f32 v72, v109, v69

	global_store_short v76, v72, s[28:29]
	v_cvt_pk_bf16_f32 v72, v150, v69

	global_store_short v76, v72, s[30:31]
	v_xor_b32_e32 v72, 0x80000000, v143

	v_cvt_pk_bf16_f32 v72, v72, v69
	global_store_short v76, v72, s[34:35]
	v_lshl_add_u64 v[78:79], s[16:17], 0, v[76:77]

	v_cvt_pk_bf16_f32 v72, v112, v69
	global_store_short v[78:79], v72, off
	v_cvt_pk_bf16_f32 v70, v70, v69
	global_store_short v76, v70, s[18:19]
	s_and_saveexec_b64 s[4:5], vcc

	v_add_f32_e32 v70, v159, v160
	v_lshl_add_u64 v[76:77], v[86:87], 4, v[124:125]
	global_store_dword v[76:77], v70, off
.LBB0_1203:
	s_or_b64 exec, exec, s[4:5]
	v_add_f32_e32 v70, v132, v75
	v_mul_f32_e32 v70, 0xbfb8aa3b, v70
	v_exp_f32_e32 v70, v70
	v_lshlrev_b64 v[74:75], 8, v[80:81]
	v_or_b32_sdwa v74, v74, v139 dst_sel:DWORD dst_unused:UNUSED_PAD src0_sel:DWORD src1_sel:BYTE_0
	v_lshl_add_u64 v[76:77], v[74:75], 2, s[14:15]
	v_add_f32_e32 v70, 1.0, v70
	v_rcp_f32_e32 v70, v70
	v_lshlrev_b64 v[74:75], 1, v[74:75]

	s_waitcnt lgkmcnt(1)
	v_add_f32_e32 v82, v171, v172
	v_mul_f32_e32 v70, 0xbf1b4598, v70
	v_mul_f32_e32 v70, 0x3fb8aa3b, v70
	v_exp_f32_e32 v70, v70
	v_mul_f32_e32 v68, v68, v144
	v_mul_f32_e32 v72, v103, v144
	v_fma_f32 v68, v143, v82, -v68
	global_store_dword v[76:77], v70, off
	v_cvt_pk_bf16_f32 v70, v84, v69

	global_store_short v74, v70, s[26:27]
	v_cvt_pk_bf16_f32 v70, v85, v69
	global_store_short v74, v70, s[28:29]

	v_cvt_pk_bf16_f32 v70, v72, v69
	global_store_short v74, v70, s[30:31]

	v_cvt_pk_bf16_f32 v68, v68, v69
	global_store_short v74, v68, s[34:35]
	s_and_saveexec_b64 s[4:5], vcc

	s_waitcnt lgkmcnt(0)
	v_add_f32_e32 v68, v166, v167
	v_lshl_add_u64 v[76:77], v[80:81], 4, v[118:119]
	v_xor_b32_e32 v68, 0x80000000, v68
	global_store_dword v[76:77], v68, off
